# gMLP task: loads batched (28 in flight) instead of ~40 serialized round trips per task; adaLN GEMV ring of 32 loads in flight
# speedup vs baseline: 1.0926x; 1.0043x over previous
.LBB0_16:
	s_mul_hi_i32 s6, s18, 0x2aaaaaab
	s_lshr_b32 s7, s6, 31
	s_ashr_i32 s19, s6, 4
	s_add_i32 s19, s19, s7
	s_mul_i32 s6, s19, 0x60
	s_sub_i32 s6, s18, s6
	s_lshl_b32 s22, s6, 6
	s_ashr_i32 s23, s22, 31
	s_mul_i32 s21, s19, 0x3000000
	s_lshl_b64 s[6:7], s[22:23], 2
	s_mul_hi_i32 s20, s19, 0x3000000
	s_add_u32 s6, s21, s6
	s_addc_u32 s7, s20, s7
	v_mov_b32_e32 v8, 0
	v_lshl_add_u64 v[10:11], v[6:7], 0, s[6:7]
	s_mov_b32 s20, 0
	v_mov_b32_e32 v12, 0
	v_mov_b32_e32 v13, v8
	v_mov_b32_e32 v14, 0
	v_mov_b32_e32 v15, v8
	v_mov_b32_e32 v16, 0
	v_mov_b32_e32 v17, v8
	v_mov_b32_e32 v18, 0
	v_mov_b32_e32 v19, v8
	s_add_u32 s24, s70, s6
	s_addc_u32 s25, s71, s7
	s_add_u32 s26, s24, 0x12000
	v_subrev_u32_e32 v142, s26, v10
	global_load_dword v78, v142, s[24:25]
	s_add_u32 s24, s24, 0x6000
	s_addc_u32 s25, s25, 0
	global_load_dword v80, v142, s[24:25]
	s_add_u32 s24, s24, 0x6000
	s_addc_u32 s25, s25, 0
	global_load_dword v82, v142, s[24:25]
	s_add_u32 s24, s24, 0x6000
	s_addc_u32 s25, s25, 0
	global_load_dword v84, v142, s[24:25]
	s_add_u32 s24, s24, 0x6000
	s_addc_u32 s25, s25, 0
	global_load_dword v86, v142, s[24:25]
	s_add_u32 s24, s24, 0x6000
	s_addc_u32 s25, s25, 0
	global_load_dword v88, v142, s[24:25]
	s_add_u32 s24, s24, 0x6000
	s_addc_u32 s25, s25, 0
	global_load_dword v90, v142, s[24:25]
	s_add_u32 s24, s24, 0x6000
	s_addc_u32 s25, s25, 0
	global_load_dword v92, v142, s[24:25]
	s_add_u32 s24, s24, 0x6000
	s_addc_u32 s25, s25, 0
	global_load_dword v94, v142, s[24:25]
	s_add_u32 s24, s24, 0x6000
	s_addc_u32 s25, s25, 0
	global_load_dword v96, v142, s[24:25]
	s_add_u32 s24, s24, 0x6000
	s_addc_u32 s25, s25, 0
	global_load_dword v98, v142, s[24:25]
	s_add_u32 s24, s24, 0x6000
	s_addc_u32 s25, s25, 0
	global_load_dword v100, v142, s[24:25]
	s_add_u32 s24, s24, 0x6000
	s_addc_u32 s25, s25, 0
	global_load_dword v102, v142, s[24:25]
	s_add_u32 s24, s24, 0x6000
	s_addc_u32 s25, s25, 0
	global_load_dword v104, v142, s[24:25]
	s_add_u32 s24, s24, 0x6000
	s_addc_u32 s25, s25, 0
	global_load_dword v106, v142, s[24:25]
	s_add_u32 s24, s24, 0x6000
	s_addc_u32 s25, s25, 0
	global_load_dword v108, v142, s[24:25]
	s_add_u32 s24, s24, 0x6000
	s_addc_u32 s25, s25, 0
	global_load_dword v110, v142, s[24:25]
	s_add_u32 s24, s24, 0x6000
	s_addc_u32 s25, s25, 0
	global_load_dword v112, v142, s[24:25]
	s_add_u32 s24, s24, 0x6000
	s_addc_u32 s25, s25, 0
	global_load_dword v114, v142, s[24:25]
	s_add_u32 s24, s24, 0x6000
	s_addc_u32 s25, s25, 0
	global_load_dword v116, v142, s[24:25]
	s_add_u32 s24, s24, 0x6000
	s_addc_u32 s25, s25, 0
	global_load_dword v118, v142, s[24:25]
	s_add_u32 s24, s24, 0x6000
	s_addc_u32 s25, s25, 0
	global_load_dword v120, v142, s[24:25]
	s_add_u32 s24, s24, 0x6000
	s_addc_u32 s25, s25, 0
	global_load_dword v122, v142, s[24:25]
	s_add_u32 s24, s24, 0x6000
	s_addc_u32 s25, s25, 0
	global_load_dword v124, v142, s[24:25]
	s_add_u32 s24, s24, 0x6000
	s_addc_u32 s25, s25, 0
	global_load_dword v126, v142, s[24:25]
	s_add_u32 s24, s24, 0x6000
	s_addc_u32 s25, s25, 0
	global_load_dword v128, v142, s[24:25]
	s_add_u32 s24, s24, 0x6000
	s_addc_u32 s25, s25, 0
	global_load_dword v130, v142, s[24:25]
	s_add_u32 s24, s24, 0x6000
	s_addc_u32 s25, s25, 0
	global_load_dword v132, v142, s[24:25]
	s_add_u32 s24, s24, 0x6000
	s_addc_u32 s25, s25, 0
	global_load_dword v134, v142, s[24:25]
	s_add_u32 s24, s24, 0x6000
	s_addc_u32 s25, s25, 0
	global_load_dword v136, v142, s[24:25]
	s_add_u32 s24, s24, 0x6000
	s_addc_u32 s25, s25, 0
	global_load_dword v138, v142, s[24:25]
	s_add_u32 s24, s24, 0x6000
	s_addc_u32 s25, s25, 0
	global_load_dword v140, v142, s[24:25]
	s_add_u32 s24, s24, 0x6000
	s_addc_u32 s25, s25, 0
	s_mov_b32 s27, 0
.Lada_loop:
	s_waitcnt vmcnt(28)
	v_add_u32_e32 v25, s20, v23
	ds_read_b128 v[26:29], v25
	ds_read_b128 v[30:33], v25 offset:8192
	ds_read_b128 v[34:37], v25 offset:16384
	ds_read_b128 v[38:41], v25 offset:24576
	ds_read_b128 v[42:45], v25 offset:32768
	ds_read_b128 v[46:49], v25 offset:40960
	ds_read_b128 v[50:53], v25 offset:49152
	ds_read_b128 v[54:57], v25 offset:57344
	v_add_u32_e32 v25, 0x10000, v25
	ds_read_b128 v[58:61], v25
	s_waitcnt lgkmcnt(6)
	v_mov_b32_e32 v70, v34
	v_mov_b32_e32 v71, v30
	v_mov_b32_e32 v72, v26
	s_waitcnt lgkmcnt(5)
	v_mov_b32_e32 v73, v38
	s_waitcnt lgkmcnt(4)
	v_mov_b32_e32 v74, v42
	s_waitcnt lgkmcnt(3)
	v_mov_b32_e32 v75, v46
	s_waitcnt lgkmcnt(2)
	v_mov_b32_e32 v76, v50
	s_waitcnt lgkmcnt(1)
	v_mov_b32_e32 v77, v54
	v_mov_b32_e32 v30, v35
	v_mov_b32_e32 v38, v27
	v_mov_b32_e32 v46, v43
	v_mov_b32_e32 v54, v51
	v_mov_b32_e32 v26, v36
	v_mov_b32_e32 v27, v32
	v_mov_b32_e32 v34, v28
	v_mov_b32_e32 v35, v40
	v_mov_b32_e32 v42, v44
	v_mov_b32_e32 v43, v48
	v_mov_b32_e32 v50, v52
	v_mov_b32_e32 v51, v56
	s_add_i32 s20, s20, 16
	v_mov_b32_e32 v32, v37
	v_mov_b32_e32 v40, v29
	v_mov_b32_e32 v48, v45
	v_mov_b32_e32 v56, v53
	v_pk_fma_f32 v[12:13], v[78:79], v[70:71], v[12:13] op_sel_hi:[0,1,1]
	v_pk_fma_f32 v[14:15], v[78:79], v[72:73], v[14:15] op_sel_hi:[0,1,1]
	v_pk_fma_f32 v[16:17], v[78:79], v[74:75], v[16:17] op_sel_hi:[0,1,1]
	v_pk_fma_f32 v[18:19], v[78:79], v[76:77], v[18:19] op_sel_hi:[0,1,1]
	s_waitcnt lgkmcnt(0)
	v_fmac_f32_e32 v8, v78, v58
	v_pk_fma_f32 v[12:13], v[80:81], v[30:31], v[12:13] op_sel_hi:[0,1,1]
	v_pk_fma_f32 v[14:15], v[80:81], v[38:39], v[14:15] op_sel_hi:[0,1,1]
	v_pk_fma_f32 v[16:17], v[80:81], v[46:47], v[16:17] op_sel_hi:[0,1,1]
	v_pk_fma_f32 v[18:19], v[80:81], v[54:55], v[18:19] op_sel_hi:[0,1,1]
	v_fmac_f32_e32 v8, v80, v59
	v_pk_fma_f32 v[12:13], v[82:83], v[26:27], v[12:13] op_sel_hi:[0,1,1]
	v_pk_fma_f32 v[14:15], v[82:83], v[34:35], v[14:15] op_sel_hi:[0,1,1]
	v_pk_fma_f32 v[16:17], v[82:83], v[42:43], v[16:17] op_sel_hi:[0,1,1]
	v_pk_fma_f32 v[18:19], v[82:83], v[50:51], v[18:19] op_sel_hi:[0,1,1]
	v_fmac_f32_e32 v8, v82, v60
	v_pk_fma_f32 v[12:13], v[84:85], v[32:33], v[12:13] op_sel_hi:[0,1,1]
	v_pk_fma_f32 v[14:15], v[84:85], v[40:41], v[14:15] op_sel_hi:[0,1,1]
	v_pk_fma_f32 v[16:17], v[84:85], v[48:49], v[16:17] op_sel_hi:[0,1,1]
	v_pk_fma_f32 v[18:19], v[84:85], v[56:57], v[18:19] op_sel_hi:[0,1,1]
	v_fmac_f32_e32 v8, v84, v61
	global_load_dword v78, v142, s[24:25]
	s_add_u32 s24, s24, 0x6000
	s_addc_u32 s25, s25, 0
	global_load_dword v80, v142, s[24:25]
	s_add_u32 s24, s24, 0x6000
	s_addc_u32 s25, s25, 0
	global_load_dword v82, v142, s[24:25]
	s_add_u32 s24, s24, 0x6000
	s_addc_u32 s25, s25, 0
	global_load_dword v84, v142, s[24:25]
	s_add_u32 s24, s24, 0x6000
	s_addc_u32 s25, s25, 0
	s_waitcnt vmcnt(28)
	v_add_u32_e32 v25, s20, v23
	ds_read_b128 v[26:29], v25
	ds_read_b128 v[30:33], v25 offset:8192
	ds_read_b128 v[34:37], v25 offset:16384
	ds_read_b128 v[38:41], v25 offset:24576
	ds_read_b128 v[42:45], v25 offset:32768
	ds_read_b128 v[46:49], v25 offset:40960
	ds_read_b128 v[50:53], v25 offset:49152
	ds_read_b128 v[54:57], v25 offset:57344
	v_add_u32_e32 v25, 0x10000, v25
	ds_read_b128 v[58:61], v25
	s_waitcnt lgkmcnt(6)
	v_mov_b32_e32 v70, v34
	v_mov_b32_e32 v71, v30
	v_mov_b32_e32 v72, v26
	s_waitcnt lgkmcnt(5)
	v_mov_b32_e32 v73, v38
	s_waitcnt lgkmcnt(4)
	v_mov_b32_e32 v74, v42
	s_waitcnt lgkmcnt(3)
	v_mov_b32_e32 v75, v46
	s_waitcnt lgkmcnt(2)
	v_mov_b32_e32 v76, v50
	s_waitcnt lgkmcnt(1)
	v_mov_b32_e32 v77, v54
	v_mov_b32_e32 v30, v35
	v_mov_b32_e32 v38, v27
	v_mov_b32_e32 v46, v43
	v_mov_b32_e32 v54, v51
	v_mov_b32_e32 v26, v36
	v_mov_b32_e32 v27, v32
	v_mov_b32_e32 v34, v28
	v_mov_b32_e32 v35, v40
	v_mov_b32_e32 v42, v44
	v_mov_b32_e32 v43, v48
	v_mov_b32_e32 v50, v52
	v_mov_b32_e32 v51, v56
	s_add_i32 s20, s20, 16
	v_mov_b32_e32 v32, v37
	v_mov_b32_e32 v40, v29
	v_mov_b32_e32 v48, v45
	v_mov_b32_e32 v56, v53
	v_pk_fma_f32 v[12:13], v[86:87], v[70:71], v[12:13] op_sel_hi:[0,1,1]
	v_pk_fma_f32 v[14:15], v[86:87], v[72:73], v[14:15] op_sel_hi:[0,1,1]
	v_pk_fma_f32 v[16:17], v[86:87], v[74:75], v[16:17] op_sel_hi:[0,1,1]
	v_pk_fma_f32 v[18:19], v[86:87], v[76:77], v[18:19] op_sel_hi:[0,1,1]
	s_waitcnt lgkmcnt(0)
	v_fmac_f32_e32 v8, v86, v58
	v_pk_fma_f32 v[12:13], v[88:89], v[30:31], v[12:13] op_sel_hi:[0,1,1]
	v_pk_fma_f32 v[14:15], v[88:89], v[38:39], v[14:15] op_sel_hi:[0,1,1]
	v_pk_fma_f32 v[16:17], v[88:89], v[46:47], v[16:17] op_sel_hi:[0,1,1]
	v_pk_fma_f32 v[18:19], v[88:89], v[54:55], v[18:19] op_sel_hi:[0,1,1]
	v_fmac_f32_e32 v8, v88, v59
	v_pk_fma_f32 v[12:13], v[90:91], v[26:27], v[12:13] op_sel_hi:[0,1,1]
	v_pk_fma_f32 v[14:15], v[90:91], v[34:35], v[14:15] op_sel_hi:[0,1,1]
	v_pk_fma_f32 v[16:17], v[90:91], v[42:43], v[16:17] op_sel_hi:[0,1,1]
	v_pk_fma_f32 v[18:19], v[90:91], v[50:51], v[18:19] op_sel_hi:[0,1,1]
	v_fmac_f32_e32 v8, v90, v60
	v_pk_fma_f32 v[12:13], v[92:93], v[32:33], v[12:13] op_sel_hi:[0,1,1]
	v_pk_fma_f32 v[14:15], v[92:93], v[40:41], v[14:15] op_sel_hi:[0,1,1]
	v_pk_fma_f32 v[16:17], v[92:93], v[48:49], v[16:17] op_sel_hi:[0,1,1]
	v_pk_fma_f32 v[18:19], v[92:93], v[56:57], v[18:19] op_sel_hi:[0,1,1]
	v_fmac_f32_e32 v8, v92, v61
	global_load_dword v86, v142, s[24:25]
	s_add_u32 s24, s24, 0x6000
	s_addc_u32 s25, s25, 0
	global_load_dword v88, v142, s[24:25]
	s_add_u32 s24, s24, 0x6000
	s_addc_u32 s25, s25, 0
	global_load_dword v90, v142, s[24:25]
	s_add_u32 s24, s24, 0x6000
	s_addc_u32 s25, s25, 0
	global_load_dword v92, v142, s[24:25]
	s_add_u32 s24, s24, 0x6000
	s_addc_u32 s25, s25, 0
	s_waitcnt vmcnt(28)
	v_add_u32_e32 v25, s20, v23
	ds_read_b128 v[26:29], v25
	ds_read_b128 v[30:33], v25 offset:8192
	ds_read_b128 v[34:37], v25 offset:16384
	ds_read_b128 v[38:41], v25 offset:24576
	ds_read_b128 v[42:45], v25 offset:32768
	ds_read_b128 v[46:49], v25 offset:40960
	ds_read_b128 v[50:53], v25 offset:49152
	ds_read_b128 v[54:57], v25 offset:57344
	v_add_u32_e32 v25, 0x10000, v25
	ds_read_b128 v[58:61], v25
	s_waitcnt lgkmcnt(6)
	v_mov_b32_e32 v70, v34
	v_mov_b32_e32 v71, v30
	v_mov_b32_e32 v72, v26
	s_waitcnt lgkmcnt(5)
	v_mov_b32_e32 v73, v38
	s_waitcnt lgkmcnt(4)
	v_mov_b32_e32 v74, v42
	s_waitcnt lgkmcnt(3)
	v_mov_b32_e32 v75, v46
	s_waitcnt lgkmcnt(2)
	v_mov_b32_e32 v76, v50
	s_waitcnt lgkmcnt(1)
	v_mov_b32_e32 v77, v54
	v_mov_b32_e32 v30, v35
	v_mov_b32_e32 v38, v27
	v_mov_b32_e32 v46, v43
	v_mov_b32_e32 v54, v51
	v_mov_b32_e32 v26, v36
	v_mov_b32_e32 v27, v32
	v_mov_b32_e32 v34, v28
	v_mov_b32_e32 v35, v40
	v_mov_b32_e32 v42, v44
	v_mov_b32_e32 v43, v48
	v_mov_b32_e32 v50, v52
	v_mov_b32_e32 v51, v56
	s_add_i32 s20, s20, 16
	v_mov_b32_e32 v32, v37
	v_mov_b32_e32 v40, v29
	v_mov_b32_e32 v48, v45
	v_mov_b32_e32 v56, v53
	v_pk_fma_f32 v[12:13], v[94:95], v[70:71], v[12:13] op_sel_hi:[0,1,1]
	v_pk_fma_f32 v[14:15], v[94:95], v[72:73], v[14:15] op_sel_hi:[0,1,1]
	v_pk_fma_f32 v[16:17], v[94:95], v[74:75], v[16:17] op_sel_hi:[0,1,1]
	v_pk_fma_f32 v[18:19], v[94:95], v[76:77], v[18:19] op_sel_hi:[0,1,1]
	s_waitcnt lgkmcnt(0)
	v_fmac_f32_e32 v8, v94, v58
	v_pk_fma_f32 v[12:13], v[96:97], v[30:31], v[12:13] op_sel_hi:[0,1,1]
	v_pk_fma_f32 v[14:15], v[96:97], v[38:39], v[14:15] op_sel_hi:[0,1,1]
	v_pk_fma_f32 v[16:17], v[96:97], v[46:47], v[16:17] op_sel_hi:[0,1,1]
	v_pk_fma_f32 v[18:19], v[96:97], v[54:55], v[18:19] op_sel_hi:[0,1,1]
	v_fmac_f32_e32 v8, v96, v59
	v_pk_fma_f32 v[12:13], v[98:99], v[26:27], v[12:13] op_sel_hi:[0,1,1]
	v_pk_fma_f32 v[14:15], v[98:99], v[34:35], v[14:15] op_sel_hi:[0,1,1]
	v_pk_fma_f32 v[16:17], v[98:99], v[42:43], v[16:17] op_sel_hi:[0,1,1]
	v_pk_fma_f32 v[18:19], v[98:99], v[50:51], v[18:19] op_sel_hi:[0,1,1]
	v_fmac_f32_e32 v8, v98, v60
	v_pk_fma_f32 v[12:13], v[100:101], v[32:33], v[12:13] op_sel_hi:[0,1,1]
	v_pk_fma_f32 v[14:15], v[100:101], v[40:41], v[14:15] op_sel_hi:[0,1,1]
	v_pk_fma_f32 v[16:17], v[100:101], v[48:49], v[16:17] op_sel_hi:[0,1,1]
	v_pk_fma_f32 v[18:19], v[100:101], v[56:57], v[18:19] op_sel_hi:[0,1,1]
	v_fmac_f32_e32 v8, v100, v61
	global_load_dword v94, v142, s[24:25]
	s_add_u32 s24, s24, 0x6000
	s_addc_u32 s25, s25, 0
	global_load_dword v96, v142, s[24:25]
	s_add_u32 s24, s24, 0x6000
	s_addc_u32 s25, s25, 0
	global_load_dword v98, v142, s[24:25]
	s_add_u32 s24, s24, 0x6000
	s_addc_u32 s25, s25, 0
	global_load_dword v100, v142, s[24:25]
	s_add_u32 s24, s24, 0x6000
	s_addc_u32 s25, s25, 0
	s_waitcnt vmcnt(28)
	v_add_u32_e32 v25, s20, v23
	ds_read_b128 v[26:29], v25
	ds_read_b128 v[30:33], v25 offset:8192
	ds_read_b128 v[34:37], v25 offset:16384
	ds_read_b128 v[38:41], v25 offset:24576
	ds_read_b128 v[42:45], v25 offset:32768
	ds_read_b128 v[46:49], v25 offset:40960
	ds_read_b128 v[50:53], v25 offset:49152
	ds_read_b128 v[54:57], v25 offset:57344
	v_add_u32_e32 v25, 0x10000, v25
	ds_read_b128 v[58:61], v25
	s_waitcnt lgkmcnt(6)
	v_mov_b32_e32 v70, v34
	v_mov_b32_e32 v71, v30
	v_mov_b32_e32 v72, v26
	s_waitcnt lgkmcnt(5)
	v_mov_b32_e32 v73, v38
	s_waitcnt lgkmcnt(4)
	v_mov_b32_e32 v74, v42
	s_waitcnt lgkmcnt(3)
	v_mov_b32_e32 v75, v46
	s_waitcnt lgkmcnt(2)
	v_mov_b32_e32 v76, v50
	s_waitcnt lgkmcnt(1)
	v_mov_b32_e32 v77, v54
	v_mov_b32_e32 v30, v35
	v_mov_b32_e32 v38, v27
	v_mov_b32_e32 v46, v43
	v_mov_b32_e32 v54, v51
	v_mov_b32_e32 v26, v36
	v_mov_b32_e32 v27, v32
	v_mov_b32_e32 v34, v28
	v_mov_b32_e32 v35, v40
	v_mov_b32_e32 v42, v44
	v_mov_b32_e32 v43, v48
	v_mov_b32_e32 v50, v52
	v_mov_b32_e32 v51, v56
	s_add_i32 s20, s20, 16
	v_mov_b32_e32 v32, v37
	v_mov_b32_e32 v40, v29
	v_mov_b32_e32 v48, v45
	v_mov_b32_e32 v56, v53
	v_pk_fma_f32 v[12:13], v[102:103], v[70:71], v[12:13] op_sel_hi:[0,1,1]
	v_pk_fma_f32 v[14:15], v[102:103], v[72:73], v[14:15] op_sel_hi:[0,1,1]
	v_pk_fma_f32 v[16:17], v[102:103], v[74:75], v[16:17] op_sel_hi:[0,1,1]
	v_pk_fma_f32 v[18:19], v[102:103], v[76:77], v[18:19] op_sel_hi:[0,1,1]
	s_waitcnt lgkmcnt(0)
	v_fmac_f32_e32 v8, v102, v58
	v_pk_fma_f32 v[12:13], v[104:105], v[30:31], v[12:13] op_sel_hi:[0,1,1]
	v_pk_fma_f32 v[14:15], v[104:105], v[38:39], v[14:15] op_sel_hi:[0,1,1]
	v_pk_fma_f32 v[16:17], v[104:105], v[46:47], v[16:17] op_sel_hi:[0,1,1]
	v_pk_fma_f32 v[18:19], v[104:105], v[54:55], v[18:19] op_sel_hi:[0,1,1]
	v_fmac_f32_e32 v8, v104, v59
	v_pk_fma_f32 v[12:13], v[106:107], v[26:27], v[12:13] op_sel_hi:[0,1,1]
	v_pk_fma_f32 v[14:15], v[106:107], v[34:35], v[14:15] op_sel_hi:[0,1,1]
	v_pk_fma_f32 v[16:17], v[106:107], v[42:43], v[16:17] op_sel_hi:[0,1,1]
	v_pk_fma_f32 v[18:19], v[106:107], v[50:51], v[18:19] op_sel_hi:[0,1,1]
	v_fmac_f32_e32 v8, v106, v60
	v_pk_fma_f32 v[12:13], v[108:109], v[32:33], v[12:13] op_sel_hi:[0,1,1]
	v_pk_fma_f32 v[14:15], v[108:109], v[40:41], v[14:15] op_sel_hi:[0,1,1]
	v_pk_fma_f32 v[16:17], v[108:109], v[48:49], v[16:17] op_sel_hi:[0,1,1]
	v_pk_fma_f32 v[18:19], v[108:109], v[56:57], v[18:19] op_sel_hi:[0,1,1]
	v_fmac_f32_e32 v8, v108, v61
	global_load_dword v102, v142, s[24:25]
	s_add_u32 s24, s24, 0x6000
	s_addc_u32 s25, s25, 0
	global_load_dword v104, v142, s[24:25]
	s_add_u32 s24, s24, 0x6000
	s_addc_u32 s25, s25, 0
	global_load_dword v106, v142, s[24:25]
	s_add_u32 s24, s24, 0x6000
	s_addc_u32 s25, s25, 0
	global_load_dword v108, v142, s[24:25]
	s_add_u32 s24, s24, 0x6000
	s_addc_u32 s25, s25, 0
	s_waitcnt vmcnt(28)
	v_add_u32_e32 v25, s20, v23
	ds_read_b128 v[26:29], v25
	ds_read_b128 v[30:33], v25 offset:8192
	ds_read_b128 v[34:37], v25 offset:16384
	ds_read_b128 v[38:41], v25 offset:24576
	ds_read_b128 v[42:45], v25 offset:32768
	ds_read_b128 v[46:49], v25 offset:40960
	ds_read_b128 v[50:53], v25 offset:49152
	ds_read_b128 v[54:57], v25 offset:57344
	v_add_u32_e32 v25, 0x10000, v25
	ds_read_b128 v[58:61], v25
	s_waitcnt lgkmcnt(6)
	v_mov_b32_e32 v70, v34
	v_mov_b32_e32 v71, v30
	v_mov_b32_e32 v72, v26
	s_waitcnt lgkmcnt(5)
	v_mov_b32_e32 v73, v38
	s_waitcnt lgkmcnt(4)
	v_mov_b32_e32 v74, v42
	s_waitcnt lgkmcnt(3)
	v_mov_b32_e32 v75, v46
	s_waitcnt lgkmcnt(2)
	v_mov_b32_e32 v76, v50
	s_waitcnt lgkmcnt(1)
	v_mov_b32_e32 v77, v54
	v_mov_b32_e32 v30, v35
	v_mov_b32_e32 v38, v27
	v_mov_b32_e32 v46, v43
	v_mov_b32_e32 v54, v51
	v_mov_b32_e32 v26, v36
	v_mov_b32_e32 v27, v32
	v_mov_b32_e32 v34, v28
	v_mov_b32_e32 v35, v40
	v_mov_b32_e32 v42, v44
	v_mov_b32_e32 v43, v48
	v_mov_b32_e32 v50, v52
	v_mov_b32_e32 v51, v56
	s_add_i32 s20, s20, 16
	v_mov_b32_e32 v32, v37
	v_mov_b32_e32 v40, v29
	v_mov_b32_e32 v48, v45
	v_mov_b32_e32 v56, v53
	v_pk_fma_f32 v[12:13], v[110:111], v[70:71], v[12:13] op_sel_hi:[0,1,1]
	v_pk_fma_f32 v[14:15], v[110:111], v[72:73], v[14:15] op_sel_hi:[0,1,1]
	v_pk_fma_f32 v[16:17], v[110:111], v[74:75], v[16:17] op_sel_hi:[0,1,1]
	v_pk_fma_f32 v[18:19], v[110:111], v[76:77], v[18:19] op_sel_hi:[0,1,1]
	s_waitcnt lgkmcnt(0)
	v_fmac_f32_e32 v8, v110, v58
	v_pk_fma_f32 v[12:13], v[112:113], v[30:31], v[12:13] op_sel_hi:[0,1,1]
	v_pk_fma_f32 v[14:15], v[112:113], v[38:39], v[14:15] op_sel_hi:[0,1,1]
	v_pk_fma_f32 v[16:17], v[112:113], v[46:47], v[16:17] op_sel_hi:[0,1,1]
	v_pk_fma_f32 v[18:19], v[112:113], v[54:55], v[18:19] op_sel_hi:[0,1,1]
	v_fmac_f32_e32 v8, v112, v59
	v_pk_fma_f32 v[12:13], v[114:115], v[26:27], v[12:13] op_sel_hi:[0,1,1]
	v_pk_fma_f32 v[14:15], v[114:115], v[34:35], v[14:15] op_sel_hi:[0,1,1]
	v_pk_fma_f32 v[16:17], v[114:115], v[42:43], v[16:17] op_sel_hi:[0,1,1]
	v_pk_fma_f32 v[18:19], v[114:115], v[50:51], v[18:19] op_sel_hi:[0,1,1]
	v_fmac_f32_e32 v8, v114, v60
	v_pk_fma_f32 v[12:13], v[116:117], v[32:33], v[12:13] op_sel_hi:[0,1,1]
	v_pk_fma_f32 v[14:15], v[116:117], v[40:41], v[14:15] op_sel_hi:[0,1,1]
	v_pk_fma_f32 v[16:17], v[116:117], v[48:49], v[16:17] op_sel_hi:[0,1,1]
	v_pk_fma_f32 v[18:19], v[116:117], v[56:57], v[18:19] op_sel_hi:[0,1,1]
	v_fmac_f32_e32 v8, v116, v61
	global_load_dword v110, v142, s[24:25]
	s_add_u32 s24, s24, 0x6000
	s_addc_u32 s25, s25, 0
	global_load_dword v112, v142, s[24:25]
	s_add_u32 s24, s24, 0x6000
	s_addc_u32 s25, s25, 0
	global_load_dword v114, v142, s[24:25]
	s_add_u32 s24, s24, 0x6000
	s_addc_u32 s25, s25, 0
	global_load_dword v116, v142, s[24:25]
	s_add_u32 s24, s24, 0x6000
	s_addc_u32 s25, s25, 0
	s_waitcnt vmcnt(28)
	v_add_u32_e32 v25, s20, v23
	ds_read_b128 v[26:29], v25
	ds_read_b128 v[30:33], v25 offset:8192
	ds_read_b128 v[34:37], v25 offset:16384
	ds_read_b128 v[38:41], v25 offset:24576
	ds_read_b128 v[42:45], v25 offset:32768
	ds_read_b128 v[46:49], v25 offset:40960
	ds_read_b128 v[50:53], v25 offset:49152
	ds_read_b128 v[54:57], v25 offset:57344
	v_add_u32_e32 v25, 0x10000, v25
	ds_read_b128 v[58:61], v25
	s_waitcnt lgkmcnt(6)
	v_mov_b32_e32 v70, v34
	v_mov_b32_e32 v71, v30
	v_mov_b32_e32 v72, v26
	s_waitcnt lgkmcnt(5)
	v_mov_b32_e32 v73, v38
	s_waitcnt lgkmcnt(4)
	v_mov_b32_e32 v74, v42
	s_waitcnt lgkmcnt(3)
	v_mov_b32_e32 v75, v46
	s_waitcnt lgkmcnt(2)
	v_mov_b32_e32 v76, v50
	s_waitcnt lgkmcnt(1)
	v_mov_b32_e32 v77, v54
	v_mov_b32_e32 v30, v35
	v_mov_b32_e32 v38, v27
	v_mov_b32_e32 v46, v43
	v_mov_b32_e32 v54, v51
	v_mov_b32_e32 v26, v36
	v_mov_b32_e32 v27, v32
	v_mov_b32_e32 v34, v28
	v_mov_b32_e32 v35, v40
	v_mov_b32_e32 v42, v44
	v_mov_b32_e32 v43, v48
	v_mov_b32_e32 v50, v52
	v_mov_b32_e32 v51, v56
	s_add_i32 s20, s20, 16
	v_mov_b32_e32 v32, v37
	v_mov_b32_e32 v40, v29
	v_mov_b32_e32 v48, v45
	v_mov_b32_e32 v56, v53
	v_pk_fma_f32 v[12:13], v[118:119], v[70:71], v[12:13] op_sel_hi:[0,1,1]
	v_pk_fma_f32 v[14:15], v[118:119], v[72:73], v[14:15] op_sel_hi:[0,1,1]
	v_pk_fma_f32 v[16:17], v[118:119], v[74:75], v[16:17] op_sel_hi:[0,1,1]
	v_pk_fma_f32 v[18:19], v[118:119], v[76:77], v[18:19] op_sel_hi:[0,1,1]
	s_waitcnt lgkmcnt(0)
	v_fmac_f32_e32 v8, v118, v58
	v_pk_fma_f32 v[12:13], v[120:121], v[30:31], v[12:13] op_sel_hi:[0,1,1]
	v_pk_fma_f32 v[14:15], v[120:121], v[38:39], v[14:15] op_sel_hi:[0,1,1]
	v_pk_fma_f32 v[16:17], v[120:121], v[46:47], v[16:17] op_sel_hi:[0,1,1]
	v_pk_fma_f32 v[18:19], v[120:121], v[54:55], v[18:19] op_sel_hi:[0,1,1]
	v_fmac_f32_e32 v8, v120, v59
	v_pk_fma_f32 v[12:13], v[122:123], v[26:27], v[12:13] op_sel_hi:[0,1,1]
	v_pk_fma_f32 v[14:15], v[122:123], v[34:35], v[14:15] op_sel_hi:[0,1,1]
	v_pk_fma_f32 v[16:17], v[122:123], v[42:43], v[16:17] op_sel_hi:[0,1,1]
	v_pk_fma_f32 v[18:19], v[122:123], v[50:51], v[18:19] op_sel_hi:[0,1,1]
	v_fmac_f32_e32 v8, v122, v60
	v_pk_fma_f32 v[12:13], v[124:125], v[32:33], v[12:13] op_sel_hi:[0,1,1]
	v_pk_fma_f32 v[14:15], v[124:125], v[40:41], v[14:15] op_sel_hi:[0,1,1]
	v_pk_fma_f32 v[16:17], v[124:125], v[48:49], v[16:17] op_sel_hi:[0,1,1]
	v_pk_fma_f32 v[18:19], v[124:125], v[56:57], v[18:19] op_sel_hi:[0,1,1]
	v_fmac_f32_e32 v8, v124, v61
	global_load_dword v118, v142, s[24:25]
	s_add_u32 s24, s24, 0x6000
	s_addc_u32 s25, s25, 0
	global_load_dword v120, v142, s[24:25]
	s_add_u32 s24, s24, 0x6000
	s_addc_u32 s25, s25, 0
	global_load_dword v122, v142, s[24:25]
	s_add_u32 s24, s24, 0x6000
	s_addc_u32 s25, s25, 0
	global_load_dword v124, v142, s[24:25]
	s_add_u32 s24, s24, 0x6000
	s_addc_u32 s25, s25, 0
	s_waitcnt vmcnt(28)
	v_add_u32_e32 v25, s20, v23
	ds_read_b128 v[26:29], v25
	ds_read_b128 v[30:33], v25 offset:8192
	ds_read_b128 v[34:37], v25 offset:16384
	ds_read_b128 v[38:41], v25 offset:24576
	ds_read_b128 v[42:45], v25 offset:32768
	ds_read_b128 v[46:49], v25 offset:40960
	ds_read_b128 v[50:53], v25 offset:49152
	ds_read_b128 v[54:57], v25 offset:57344
	v_add_u32_e32 v25, 0x10000, v25
	ds_read_b128 v[58:61], v25
	s_waitcnt lgkmcnt(6)
	v_mov_b32_e32 v70, v34
	v_mov_b32_e32 v71, v30
	v_mov_b32_e32 v72, v26
	s_waitcnt lgkmcnt(5)
	v_mov_b32_e32 v73, v38
	s_waitcnt lgkmcnt(4)
	v_mov_b32_e32 v74, v42
	s_waitcnt lgkmcnt(3)
	v_mov_b32_e32 v75, v46
	s_waitcnt lgkmcnt(2)
	v_mov_b32_e32 v76, v50
	s_waitcnt lgkmcnt(1)
	v_mov_b32_e32 v77, v54
	v_mov_b32_e32 v30, v35
	v_mov_b32_e32 v38, v27
	v_mov_b32_e32 v46, v43
	v_mov_b32_e32 v54, v51
	v_mov_b32_e32 v26, v36
	v_mov_b32_e32 v27, v32
	v_mov_b32_e32 v34, v28
	v_mov_b32_e32 v35, v40
	v_mov_b32_e32 v42, v44
	v_mov_b32_e32 v43, v48
	v_mov_b32_e32 v50, v52
	v_mov_b32_e32 v51, v56
	s_add_i32 s20, s20, 16
	v_mov_b32_e32 v32, v37
	v_mov_b32_e32 v40, v29
	v_mov_b32_e32 v48, v45
	v_mov_b32_e32 v56, v53
	v_pk_fma_f32 v[12:13], v[126:127], v[70:71], v[12:13] op_sel_hi:[0,1,1]
	v_pk_fma_f32 v[14:15], v[126:127], v[72:73], v[14:15] op_sel_hi:[0,1,1]
	v_pk_fma_f32 v[16:17], v[126:127], v[74:75], v[16:17] op_sel_hi:[0,1,1]
	v_pk_fma_f32 v[18:19], v[126:127], v[76:77], v[18:19] op_sel_hi:[0,1,1]
	s_waitcnt lgkmcnt(0)
	v_fmac_f32_e32 v8, v126, v58
	v_pk_fma_f32 v[12:13], v[128:129], v[30:31], v[12:13] op_sel_hi:[0,1,1]
	v_pk_fma_f32 v[14:15], v[128:129], v[38:39], v[14:15] op_sel_hi:[0,1,1]
	v_pk_fma_f32 v[16:17], v[128:129], v[46:47], v[16:17] op_sel_hi:[0,1,1]
	v_pk_fma_f32 v[18:19], v[128:129], v[54:55], v[18:19] op_sel_hi:[0,1,1]
	v_fmac_f32_e32 v8, v128, v59
	v_pk_fma_f32 v[12:13], v[130:131], v[26:27], v[12:13] op_sel_hi:[0,1,1]
	v_pk_fma_f32 v[14:15], v[130:131], v[34:35], v[14:15] op_sel_hi:[0,1,1]
	v_pk_fma_f32 v[16:17], v[130:131], v[42:43], v[16:17] op_sel_hi:[0,1,1]
	v_pk_fma_f32 v[18:19], v[130:131], v[50:51], v[18:19] op_sel_hi:[0,1,1]
	v_fmac_f32_e32 v8, v130, v60
	v_pk_fma_f32 v[12:13], v[132:133], v[32:33], v[12:13] op_sel_hi:[0,1,1]
	v_pk_fma_f32 v[14:15], v[132:133], v[40:41], v[14:15] op_sel_hi:[0,1,1]
	v_pk_fma_f32 v[16:17], v[132:133], v[48:49], v[16:17] op_sel_hi:[0,1,1]
	v_pk_fma_f32 v[18:19], v[132:133], v[56:57], v[18:19] op_sel_hi:[0,1,1]
	v_fmac_f32_e32 v8, v132, v61
	global_load_dword v126, v142, s[24:25]
	s_add_u32 s24, s24, 0x6000
	s_addc_u32 s25, s25, 0
	global_load_dword v128, v142, s[24:25]
	s_add_u32 s24, s24, 0x6000
	s_addc_u32 s25, s25, 0
	global_load_dword v130, v142, s[24:25]
	s_add_u32 s24, s24, 0x6000
	s_addc_u32 s25, s25, 0
	global_load_dword v132, v142, s[24:25]
	s_add_u32 s24, s24, 0x6000
	s_addc_u32 s25, s25, 0
	s_waitcnt vmcnt(28)
	v_add_u32_e32 v25, s20, v23
	ds_read_b128 v[26:29], v25
	ds_read_b128 v[30:33], v25 offset:8192
	ds_read_b128 v[34:37], v25 offset:16384
	ds_read_b128 v[38:41], v25 offset:24576
	ds_read_b128 v[42:45], v25 offset:32768
	ds_read_b128 v[46:49], v25 offset:40960
	ds_read_b128 v[50:53], v25 offset:49152
	ds_read_b128 v[54:57], v25 offset:57344
	v_add_u32_e32 v25, 0x10000, v25
	ds_read_b128 v[58:61], v25
	s_waitcnt lgkmcnt(6)
	v_mov_b32_e32 v70, v34
	v_mov_b32_e32 v71, v30
	v_mov_b32_e32 v72, v26
	s_waitcnt lgkmcnt(5)
	v_mov_b32_e32 v73, v38
	s_waitcnt lgkmcnt(4)
	v_mov_b32_e32 v74, v42
	s_waitcnt lgkmcnt(3)
	v_mov_b32_e32 v75, v46
	s_waitcnt lgkmcnt(2)
	v_mov_b32_e32 v76, v50
	s_waitcnt lgkmcnt(1)
	v_mov_b32_e32 v77, v54
	v_mov_b32_e32 v30, v35
	v_mov_b32_e32 v38, v27
	v_mov_b32_e32 v46, v43
	v_mov_b32_e32 v54, v51
	v_mov_b32_e32 v26, v36
	v_mov_b32_e32 v27, v32
	v_mov_b32_e32 v34, v28
	v_mov_b32_e32 v35, v40
	v_mov_b32_e32 v42, v44
	v_mov_b32_e32 v43, v48
	v_mov_b32_e32 v50, v52
	v_mov_b32_e32 v51, v56
	s_add_i32 s20, s20, 16
	v_mov_b32_e32 v32, v37
	v_mov_b32_e32 v40, v29
	v_mov_b32_e32 v48, v45
	v_mov_b32_e32 v56, v53
	v_pk_fma_f32 v[12:13], v[134:135], v[70:71], v[12:13] op_sel_hi:[0,1,1]
	v_pk_fma_f32 v[14:15], v[134:135], v[72:73], v[14:15] op_sel_hi:[0,1,1]
	v_pk_fma_f32 v[16:17], v[134:135], v[74:75], v[16:17] op_sel_hi:[0,1,1]
	v_pk_fma_f32 v[18:19], v[134:135], v[76:77], v[18:19] op_sel_hi:[0,1,1]
	s_waitcnt lgkmcnt(0)
	v_fmac_f32_e32 v8, v134, v58
	v_pk_fma_f32 v[12:13], v[136:137], v[30:31], v[12:13] op_sel_hi:[0,1,1]
	v_pk_fma_f32 v[14:15], v[136:137], v[38:39], v[14:15] op_sel_hi:[0,1,1]
	v_pk_fma_f32 v[16:17], v[136:137], v[46:47], v[16:17] op_sel_hi:[0,1,1]
	v_pk_fma_f32 v[18:19], v[136:137], v[54:55], v[18:19] op_sel_hi:[0,1,1]
	v_fmac_f32_e32 v8, v136, v59
	v_pk_fma_f32 v[12:13], v[138:139], v[26:27], v[12:13] op_sel_hi:[0,1,1]
	v_pk_fma_f32 v[14:15], v[138:139], v[34:35], v[14:15] op_sel_hi:[0,1,1]
	v_pk_fma_f32 v[16:17], v[138:139], v[42:43], v[16:17] op_sel_hi:[0,1,1]
	v_pk_fma_f32 v[18:19], v[138:139], v[50:51], v[18:19] op_sel_hi:[0,1,1]
	v_fmac_f32_e32 v8, v138, v60
	v_pk_fma_f32 v[12:13], v[140:141], v[32:33], v[12:13] op_sel_hi:[0,1,1]
	v_pk_fma_f32 v[14:15], v[140:141], v[40:41], v[14:15] op_sel_hi:[0,1,1]
	v_pk_fma_f32 v[16:17], v[140:141], v[48:49], v[16:17] op_sel_hi:[0,1,1]
	v_pk_fma_f32 v[18:19], v[140:141], v[56:57], v[18:19] op_sel_hi:[0,1,1]
	v_fmac_f32_e32 v8, v140, v61
	global_load_dword v134, v142, s[24:25]
	s_add_u32 s24, s24, 0x6000
	s_addc_u32 s25, s25, 0
	global_load_dword v136, v142, s[24:25]
	s_add_u32 s24, s24, 0x6000
	s_addc_u32 s25, s25, 0
	global_load_dword v138, v142, s[24:25]
	s_add_u32 s24, s24, 0x6000
	s_addc_u32 s25, s25, 0
	global_load_dword v140, v142, s[24:25]
	s_add_u32 s24, s24, 0x6000
	s_addc_u32 s25, s25, 0
	s_add_i32 s27, s27, 1
	s_cmp_lt_u32 s27, 7
	s_cbranch_scc1 .Lada_loop
	s_waitcnt vmcnt(28)
	v_add_u32_e32 v25, s20, v23
	ds_read_b128 v[26:29], v25
	ds_read_b128 v[30:33], v25 offset:8192
	ds_read_b128 v[34:37], v25 offset:16384
	ds_read_b128 v[38:41], v25 offset:24576
	ds_read_b128 v[42:45], v25 offset:32768
	ds_read_b128 v[46:49], v25 offset:40960
	ds_read_b128 v[50:53], v25 offset:49152
	ds_read_b128 v[54:57], v25 offset:57344
	v_add_u32_e32 v25, 0x10000, v25
	ds_read_b128 v[58:61], v25
	s_waitcnt lgkmcnt(6)
	v_mov_b32_e32 v70, v34
	v_mov_b32_e32 v71, v30
	v_mov_b32_e32 v72, v26
	s_waitcnt lgkmcnt(5)
	v_mov_b32_e32 v73, v38
	s_waitcnt lgkmcnt(4)
	v_mov_b32_e32 v74, v42
	s_waitcnt lgkmcnt(3)
	v_mov_b32_e32 v75, v46
	s_waitcnt lgkmcnt(2)
	v_mov_b32_e32 v76, v50
	s_waitcnt lgkmcnt(1)
	v_mov_b32_e32 v77, v54
	v_mov_b32_e32 v30, v35
	v_mov_b32_e32 v38, v27
	v_mov_b32_e32 v46, v43
	v_mov_b32_e32 v54, v51
	v_mov_b32_e32 v26, v36
	v_mov_b32_e32 v27, v32
	v_mov_b32_e32 v34, v28
	v_mov_b32_e32 v35, v40
	v_mov_b32_e32 v42, v44
	v_mov_b32_e32 v43, v48
	v_mov_b32_e32 v50, v52
	v_mov_b32_e32 v51, v56
	s_add_i32 s20, s20, 16
	v_mov_b32_e32 v32, v37
	v_mov_b32_e32 v40, v29
	v_mov_b32_e32 v48, v45
	v_mov_b32_e32 v56, v53
	v_pk_fma_f32 v[12:13], v[78:79], v[70:71], v[12:13] op_sel_hi:[0,1,1]
	v_pk_fma_f32 v[14:15], v[78:79], v[72:73], v[14:15] op_sel_hi:[0,1,1]
	v_pk_fma_f32 v[16:17], v[78:79], v[74:75], v[16:17] op_sel_hi:[0,1,1]
	v_pk_fma_f32 v[18:19], v[78:79], v[76:77], v[18:19] op_sel_hi:[0,1,1]
	s_waitcnt lgkmcnt(0)
	v_fmac_f32_e32 v8, v78, v58
	v_pk_fma_f32 v[12:13], v[80:81], v[30:31], v[12:13] op_sel_hi:[0,1,1]
	v_pk_fma_f32 v[14:15], v[80:81], v[38:39], v[14:15] op_sel_hi:[0,1,1]
	v_pk_fma_f32 v[16:17], v[80:81], v[46:47], v[16:17] op_sel_hi:[0,1,1]
	v_pk_fma_f32 v[18:19], v[80:81], v[54:55], v[18:19] op_sel_hi:[0,1,1]
	v_fmac_f32_e32 v8, v80, v59
	v_pk_fma_f32 v[12:13], v[82:83], v[26:27], v[12:13] op_sel_hi:[0,1,1]
	v_pk_fma_f32 v[14:15], v[82:83], v[34:35], v[14:15] op_sel_hi:[0,1,1]
	v_pk_fma_f32 v[16:17], v[82:83], v[42:43], v[16:17] op_sel_hi:[0,1,1]
	v_pk_fma_f32 v[18:19], v[82:83], v[50:51], v[18:19] op_sel_hi:[0,1,1]
	v_fmac_f32_e32 v8, v82, v60
	v_pk_fma_f32 v[12:13], v[84:85], v[32:33], v[12:13] op_sel_hi:[0,1,1]
	v_pk_fma_f32 v[14:15], v[84:85], v[40:41], v[14:15] op_sel_hi:[0,1,1]
	v_pk_fma_f32 v[16:17], v[84:85], v[48:49], v[16:17] op_sel_hi:[0,1,1]
	v_pk_fma_f32 v[18:19], v[84:85], v[56:57], v[18:19] op_sel_hi:[0,1,1]
	v_fmac_f32_e32 v8, v84, v61
	s_waitcnt vmcnt(24)
	v_add_u32_e32 v25, s20, v23
	ds_read_b128 v[26:29], v25
	ds_read_b128 v[30:33], v25 offset:8192
	ds_read_b128 v[34:37], v25 offset:16384
	ds_read_b128 v[38:41], v25 offset:24576
	ds_read_b128 v[42:45], v25 offset:32768
	ds_read_b128 v[46:49], v25 offset:40960
	ds_read_b128 v[50:53], v25 offset:49152
	ds_read_b128 v[54:57], v25 offset:57344
	v_add_u32_e32 v25, 0x10000, v25
	ds_read_b128 v[58:61], v25
	s_waitcnt lgkmcnt(6)
	v_mov_b32_e32 v70, v34
	v_mov_b32_e32 v71, v30
	v_mov_b32_e32 v72, v26
	s_waitcnt lgkmcnt(5)
	v_mov_b32_e32 v73, v38
	s_waitcnt lgkmcnt(4)
	v_mov_b32_e32 v74, v42
	s_waitcnt lgkmcnt(3)
	v_mov_b32_e32 v75, v46
	s_waitcnt lgkmcnt(2)
	v_mov_b32_e32 v76, v50
	s_waitcnt lgkmcnt(1)
	v_mov_b32_e32 v77, v54
	v_mov_b32_e32 v30, v35
	v_mov_b32_e32 v38, v27
	v_mov_b32_e32 v46, v43
	v_mov_b32_e32 v54, v51
	v_mov_b32_e32 v26, v36
	v_mov_b32_e32 v27, v32
	v_mov_b32_e32 v34, v28
	v_mov_b32_e32 v35, v40
	v_mov_b32_e32 v42, v44
	v_mov_b32_e32 v43, v48
	v_mov_b32_e32 v50, v52
	v_mov_b32_e32 v51, v56
	s_add_i32 s20, s20, 16
	v_mov_b32_e32 v32, v37
	v_mov_b32_e32 v40, v29
	v_mov_b32_e32 v48, v45
	v_mov_b32_e32 v56, v53
	v_pk_fma_f32 v[12:13], v[86:87], v[70:71], v[12:13] op_sel_hi:[0,1,1]
	v_pk_fma_f32 v[14:15], v[86:87], v[72:73], v[14:15] op_sel_hi:[0,1,1]
	v_pk_fma_f32 v[16:17], v[86:87], v[74:75], v[16:17] op_sel_hi:[0,1,1]
	v_pk_fma_f32 v[18:19], v[86:87], v[76:77], v[18:19] op_sel_hi:[0,1,1]
	s_waitcnt lgkmcnt(0)
	v_fmac_f32_e32 v8, v86, v58
	v_pk_fma_f32 v[12:13], v[88:89], v[30:31], v[12:13] op_sel_hi:[0,1,1]
	v_pk_fma_f32 v[14:15], v[88:89], v[38:39], v[14:15] op_sel_hi:[0,1,1]
	v_pk_fma_f32 v[16:17], v[88:89], v[46:47], v[16:17] op_sel_hi:[0,1,1]
	v_pk_fma_f32 v[18:19], v[88:89], v[54:55], v[18:19] op_sel_hi:[0,1,1]
	v_fmac_f32_e32 v8, v88, v59
	v_pk_fma_f32 v[12:13], v[90:91], v[26:27], v[12:13] op_sel_hi:[0,1,1]
	v_pk_fma_f32 v[14:15], v[90:91], v[34:35], v[14:15] op_sel_hi:[0,1,1]
	v_pk_fma_f32 v[16:17], v[90:91], v[42:43], v[16:17] op_sel_hi:[0,1,1]
	v_pk_fma_f32 v[18:19], v[90:91], v[50:51], v[18:19] op_sel_hi:[0,1,1]
	v_fmac_f32_e32 v8, v90, v60
	v_pk_fma_f32 v[12:13], v[92:93], v[32:33], v[12:13] op_sel_hi:[0,1,1]
	v_pk_fma_f32 v[14:15], v[92:93], v[40:41], v[14:15] op_sel_hi:[0,1,1]
	v_pk_fma_f32 v[16:17], v[92:93], v[48:49], v[16:17] op_sel_hi:[0,1,1]
	v_pk_fma_f32 v[18:19], v[92:93], v[56:57], v[18:19] op_sel_hi:[0,1,1]
	v_fmac_f32_e32 v8, v92, v61
	s_waitcnt vmcnt(20)
	v_add_u32_e32 v25, s20, v23
	ds_read_b128 v[26:29], v25
	ds_read_b128 v[30:33], v25 offset:8192
	ds_read_b128 v[34:37], v25 offset:16384
	ds_read_b128 v[38:41], v25 offset:24576
	ds_read_b128 v[42:45], v25 offset:32768
	ds_read_b128 v[46:49], v25 offset:40960
	ds_read_b128 v[50:53], v25 offset:49152
	ds_read_b128 v[54:57], v25 offset:57344
	v_add_u32_e32 v25, 0x10000, v25
	ds_read_b128 v[58:61], v25
	s_waitcnt lgkmcnt(6)
	v_mov_b32_e32 v70, v34
	v_mov_b32_e32 v71, v30
	v_mov_b32_e32 v72, v26
	s_waitcnt lgkmcnt(5)
	v_mov_b32_e32 v73, v38
	s_waitcnt lgkmcnt(4)
	v_mov_b32_e32 v74, v42
	s_waitcnt lgkmcnt(3)
	v_mov_b32_e32 v75, v46
	s_waitcnt lgkmcnt(2)
	v_mov_b32_e32 v76, v50
	s_waitcnt lgkmcnt(1)
	v_mov_b32_e32 v77, v54
	v_mov_b32_e32 v30, v35
	v_mov_b32_e32 v38, v27
	v_mov_b32_e32 v46, v43
	v_mov_b32_e32 v54, v51
	v_mov_b32_e32 v26, v36
	v_mov_b32_e32 v27, v32
	v_mov_b32_e32 v34, v28
	v_mov_b32_e32 v35, v40
	v_mov_b32_e32 v42, v44
	v_mov_b32_e32 v43, v48
	v_mov_b32_e32 v50, v52
	v_mov_b32_e32 v51, v56
	s_add_i32 s20, s20, 16
	v_mov_b32_e32 v32, v37
	v_mov_b32_e32 v40, v29
	v_mov_b32_e32 v48, v45
	v_mov_b32_e32 v56, v53
	v_pk_fma_f32 v[12:13], v[94:95], v[70:71], v[12:13] op_sel_hi:[0,1,1]
	v_pk_fma_f32 v[14:15], v[94:95], v[72:73], v[14:15] op_sel_hi:[0,1,1]
	v_pk_fma_f32 v[16:17], v[94:95], v[74:75], v[16:17] op_sel_hi:[0,1,1]
	v_pk_fma_f32 v[18:19], v[94:95], v[76:77], v[18:19] op_sel_hi:[0,1,1]
	s_waitcnt lgkmcnt(0)
	v_fmac_f32_e32 v8, v94, v58
	v_pk_fma_f32 v[12:13], v[96:97], v[30:31], v[12:13] op_sel_hi:[0,1,1]
	v_pk_fma_f32 v[14:15], v[96:97], v[38:39], v[14:15] op_sel_hi:[0,1,1]
	v_pk_fma_f32 v[16:17], v[96:97], v[46:47], v[16:17] op_sel_hi:[0,1,1]
	v_pk_fma_f32 v[18:19], v[96:97], v[54:55], v[18:19] op_sel_hi:[0,1,1]
	v_fmac_f32_e32 v8, v96, v59
	v_pk_fma_f32 v[12:13], v[98:99], v[26:27], v[12:13] op_sel_hi:[0,1,1]
	v_pk_fma_f32 v[14:15], v[98:99], v[34:35], v[14:15] op_sel_hi:[0,1,1]
	v_pk_fma_f32 v[16:17], v[98:99], v[42:43], v[16:17] op_sel_hi:[0,1,1]
	v_pk_fma_f32 v[18:19], v[98:99], v[50:51], v[18:19] op_sel_hi:[0,1,1]
	v_fmac_f32_e32 v8, v98, v60
	v_pk_fma_f32 v[12:13], v[100:101], v[32:33], v[12:13] op_sel_hi:[0,1,1]
	v_pk_fma_f32 v[14:15], v[100:101], v[40:41], v[14:15] op_sel_hi:[0,1,1]
	v_pk_fma_f32 v[16:17], v[100:101], v[48:49], v[16:17] op_sel_hi:[0,1,1]
	v_pk_fma_f32 v[18:19], v[100:101], v[56:57], v[18:19] op_sel_hi:[0,1,1]
	v_fmac_f32_e32 v8, v100, v61
	s_waitcnt vmcnt(16)
	v_add_u32_e32 v25, s20, v23
	ds_read_b128 v[26:29], v25
	ds_read_b128 v[30:33], v25 offset:8192
	ds_read_b128 v[34:37], v25 offset:16384
	ds_read_b128 v[38:41], v25 offset:24576
	ds_read_b128 v[42:45], v25 offset:32768
	ds_read_b128 v[46:49], v25 offset:40960
	ds_read_b128 v[50:53], v25 offset:49152
	ds_read_b128 v[54:57], v25 offset:57344
	v_add_u32_e32 v25, 0x10000, v25
	ds_read_b128 v[58:61], v25
	s_waitcnt lgkmcnt(6)
	v_mov_b32_e32 v70, v34
	v_mov_b32_e32 v71, v30
	v_mov_b32_e32 v72, v26
	s_waitcnt lgkmcnt(5)
	v_mov_b32_e32 v73, v38
	s_waitcnt lgkmcnt(4)
	v_mov_b32_e32 v74, v42
	s_waitcnt lgkmcnt(3)
	v_mov_b32_e32 v75, v46
	s_waitcnt lgkmcnt(2)
	v_mov_b32_e32 v76, v50
	s_waitcnt lgkmcnt(1)
	v_mov_b32_e32 v77, v54
	v_mov_b32_e32 v30, v35
	v_mov_b32_e32 v38, v27
	v_mov_b32_e32 v46, v43
	v_mov_b32_e32 v54, v51
	v_mov_b32_e32 v26, v36
	v_mov_b32_e32 v27, v32
	v_mov_b32_e32 v34, v28
	v_mov_b32_e32 v35, v40
	v_mov_b32_e32 v42, v44
	v_mov_b32_e32 v43, v48
	v_mov_b32_e32 v50, v52
	v_mov_b32_e32 v51, v56
	s_add_i32 s20, s20, 16
	v_mov_b32_e32 v32, v37
	v_mov_b32_e32 v40, v29
	v_mov_b32_e32 v48, v45
	v_mov_b32_e32 v56, v53
	v_pk_fma_f32 v[12:13], v[102:103], v[70:71], v[12:13] op_sel_hi:[0,1,1]
	v_pk_fma_f32 v[14:15], v[102:103], v[72:73], v[14:15] op_sel_hi:[0,1,1]
	v_pk_fma_f32 v[16:17], v[102:103], v[74:75], v[16:17] op_sel_hi:[0,1,1]
	v_pk_fma_f32 v[18:19], v[102:103], v[76:77], v[18:19] op_sel_hi:[0,1,1]
	s_waitcnt lgkmcnt(0)
	v_fmac_f32_e32 v8, v102, v58
	v_pk_fma_f32 v[12:13], v[104:105], v[30:31], v[12:13] op_sel_hi:[0,1,1]
	v_pk_fma_f32 v[14:15], v[104:105], v[38:39], v[14:15] op_sel_hi:[0,1,1]
	v_pk_fma_f32 v[16:17], v[104:105], v[46:47], v[16:17] op_sel_hi:[0,1,1]
	v_pk_fma_f32 v[18:19], v[104:105], v[54:55], v[18:19] op_sel_hi:[0,1,1]
	v_fmac_f32_e32 v8, v104, v59
	v_pk_fma_f32 v[12:13], v[106:107], v[26:27], v[12:13] op_sel_hi:[0,1,1]
	v_pk_fma_f32 v[14:15], v[106:107], v[34:35], v[14:15] op_sel_hi:[0,1,1]
	v_pk_fma_f32 v[16:17], v[106:107], v[42:43], v[16:17] op_sel_hi:[0,1,1]
	v_pk_fma_f32 v[18:19], v[106:107], v[50:51], v[18:19] op_sel_hi:[0,1,1]
	v_fmac_f32_e32 v8, v106, v60
	v_pk_fma_f32 v[12:13], v[108:109], v[32:33], v[12:13] op_sel_hi:[0,1,1]
	v_pk_fma_f32 v[14:15], v[108:109], v[40:41], v[14:15] op_sel_hi:[0,1,1]
	v_pk_fma_f32 v[16:17], v[108:109], v[48:49], v[16:17] op_sel_hi:[0,1,1]
	v_pk_fma_f32 v[18:19], v[108:109], v[56:57], v[18:19] op_sel_hi:[0,1,1]
	v_fmac_f32_e32 v8, v108, v61
	s_waitcnt vmcnt(12)
	v_add_u32_e32 v25, s20, v23
	ds_read_b128 v[26:29], v25
	ds_read_b128 v[30:33], v25 offset:8192
	ds_read_b128 v[34:37], v25 offset:16384
	ds_read_b128 v[38:41], v25 offset:24576
	ds_read_b128 v[42:45], v25 offset:32768
	ds_read_b128 v[46:49], v25 offset:40960
	ds_read_b128 v[50:53], v25 offset:49152
	ds_read_b128 v[54:57], v25 offset:57344
	v_add_u32_e32 v25, 0x10000, v25
	ds_read_b128 v[58:61], v25
	s_waitcnt lgkmcnt(6)
	v_mov_b32_e32 v70, v34
	v_mov_b32_e32 v71, v30
	v_mov_b32_e32 v72, v26
	s_waitcnt lgkmcnt(5)
	v_mov_b32_e32 v73, v38
	s_waitcnt lgkmcnt(4)
	v_mov_b32_e32 v74, v42
	s_waitcnt lgkmcnt(3)
	v_mov_b32_e32 v75, v46
	s_waitcnt lgkmcnt(2)
	v_mov_b32_e32 v76, v50
	s_waitcnt lgkmcnt(1)
	v_mov_b32_e32 v77, v54
	v_mov_b32_e32 v30, v35
	v_mov_b32_e32 v38, v27
	v_mov_b32_e32 v46, v43
	v_mov_b32_e32 v54, v51
	v_mov_b32_e32 v26, v36
	v_mov_b32_e32 v27, v32
	v_mov_b32_e32 v34, v28
	v_mov_b32_e32 v35, v40
	v_mov_b32_e32 v42, v44
	v_mov_b32_e32 v43, v48
	v_mov_b32_e32 v50, v52
	v_mov_b32_e32 v51, v56
	s_add_i32 s20, s20, 16
	v_mov_b32_e32 v32, v37
	v_mov_b32_e32 v40, v29
	v_mov_b32_e32 v48, v45
	v_mov_b32_e32 v56, v53
	v_pk_fma_f32 v[12:13], v[110:111], v[70:71], v[12:13] op_sel_hi:[0,1,1]
	v_pk_fma_f32 v[14:15], v[110:111], v[72:73], v[14:15] op_sel_hi:[0,1,1]
	v_pk_fma_f32 v[16:17], v[110:111], v[74:75], v[16:17] op_sel_hi:[0,1,1]
	v_pk_fma_f32 v[18:19], v[110:111], v[76:77], v[18:19] op_sel_hi:[0,1,1]
	s_waitcnt lgkmcnt(0)
	v_fmac_f32_e32 v8, v110, v58
	v_pk_fma_f32 v[12:13], v[112:113], v[30:31], v[12:13] op_sel_hi:[0,1,1]
	v_pk_fma_f32 v[14:15], v[112:113], v[38:39], v[14:15] op_sel_hi:[0,1,1]
	v_pk_fma_f32 v[16:17], v[112:113], v[46:47], v[16:17] op_sel_hi:[0,1,1]
	v_pk_fma_f32 v[18:19], v[112:113], v[54:55], v[18:19] op_sel_hi:[0,1,1]
	v_fmac_f32_e32 v8, v112, v59
	v_pk_fma_f32 v[12:13], v[114:115], v[26:27], v[12:13] op_sel_hi:[0,1,1]
	v_pk_fma_f32 v[14:15], v[114:115], v[34:35], v[14:15] op_sel_hi:[0,1,1]
	v_pk_fma_f32 v[16:17], v[114:115], v[42:43], v[16:17] op_sel_hi:[0,1,1]
	v_pk_fma_f32 v[18:19], v[114:115], v[50:51], v[18:19] op_sel_hi:[0,1,1]
	v_fmac_f32_e32 v8, v114, v60
	v_pk_fma_f32 v[12:13], v[116:117], v[32:33], v[12:13] op_sel_hi:[0,1,1]
	v_pk_fma_f32 v[14:15], v[116:117], v[40:41], v[14:15] op_sel_hi:[0,1,1]
	v_pk_fma_f32 v[16:17], v[116:117], v[48:49], v[16:17] op_sel_hi:[0,1,1]
	v_pk_fma_f32 v[18:19], v[116:117], v[56:57], v[18:19] op_sel_hi:[0,1,1]
	v_fmac_f32_e32 v8, v116, v61
	s_waitcnt vmcnt(8)
	v_add_u32_e32 v25, s20, v23
	ds_read_b128 v[26:29], v25
	ds_read_b128 v[30:33], v25 offset:8192
	ds_read_b128 v[34:37], v25 offset:16384
	ds_read_b128 v[38:41], v25 offset:24576
	ds_read_b128 v[42:45], v25 offset:32768
	ds_read_b128 v[46:49], v25 offset:40960
	ds_read_b128 v[50:53], v25 offset:49152
	ds_read_b128 v[54:57], v25 offset:57344
	v_add_u32_e32 v25, 0x10000, v25
	ds_read_b128 v[58:61], v25
	s_waitcnt lgkmcnt(6)
	v_mov_b32_e32 v70, v34
	v_mov_b32_e32 v71, v30
	v_mov_b32_e32 v72, v26
	s_waitcnt lgkmcnt(5)
	v_mov_b32_e32 v73, v38
	s_waitcnt lgkmcnt(4)
	v_mov_b32_e32 v74, v42
	s_waitcnt lgkmcnt(3)
	v_mov_b32_e32 v75, v46
	s_waitcnt lgkmcnt(2)
	v_mov_b32_e32 v76, v50
	s_waitcnt lgkmcnt(1)
	v_mov_b32_e32 v77, v54
	v_mov_b32_e32 v30, v35
	v_mov_b32_e32 v38, v27
	v_mov_b32_e32 v46, v43
	v_mov_b32_e32 v54, v51
	v_mov_b32_e32 v26, v36
	v_mov_b32_e32 v27, v32
	v_mov_b32_e32 v34, v28
	v_mov_b32_e32 v35, v40
	v_mov_b32_e32 v42, v44
	v_mov_b32_e32 v43, v48
	v_mov_b32_e32 v50, v52
	v_mov_b32_e32 v51, v56
	s_add_i32 s20, s20, 16
	v_mov_b32_e32 v32, v37
	v_mov_b32_e32 v40, v29
	v_mov_b32_e32 v48, v45
	v_mov_b32_e32 v56, v53
	v_pk_fma_f32 v[12:13], v[118:119], v[70:71], v[12:13] op_sel_hi:[0,1,1]
	v_pk_fma_f32 v[14:15], v[118:119], v[72:73], v[14:15] op_sel_hi:[0,1,1]
	v_pk_fma_f32 v[16:17], v[118:119], v[74:75], v[16:17] op_sel_hi:[0,1,1]
	v_pk_fma_f32 v[18:19], v[118:119], v[76:77], v[18:19] op_sel_hi:[0,1,1]
	s_waitcnt lgkmcnt(0)
	v_fmac_f32_e32 v8, v118, v58
	v_pk_fma_f32 v[12:13], v[120:121], v[30:31], v[12:13] op_sel_hi:[0,1,1]
	v_pk_fma_f32 v[14:15], v[120:121], v[38:39], v[14:15] op_sel_hi:[0,1,1]
	v_pk_fma_f32 v[16:17], v[120:121], v[46:47], v[16:17] op_sel_hi:[0,1,1]
	v_pk_fma_f32 v[18:19], v[120:121], v[54:55], v[18:19] op_sel_hi:[0,1,1]
	v_fmac_f32_e32 v8, v120, v59
	v_pk_fma_f32 v[12:13], v[122:123], v[26:27], v[12:13] op_sel_hi:[0,1,1]
	v_pk_fma_f32 v[14:15], v[122:123], v[34:35], v[14:15] op_sel_hi:[0,1,1]
	v_pk_fma_f32 v[16:17], v[122:123], v[42:43], v[16:17] op_sel_hi:[0,1,1]
	v_pk_fma_f32 v[18:19], v[122:123], v[50:51], v[18:19] op_sel_hi:[0,1,1]
	v_fmac_f32_e32 v8, v122, v60
	v_pk_fma_f32 v[12:13], v[124:125], v[32:33], v[12:13] op_sel_hi:[0,1,1]
	v_pk_fma_f32 v[14:15], v[124:125], v[40:41], v[14:15] op_sel_hi:[0,1,1]
	v_pk_fma_f32 v[16:17], v[124:125], v[48:49], v[16:17] op_sel_hi:[0,1,1]
	v_pk_fma_f32 v[18:19], v[124:125], v[56:57], v[18:19] op_sel_hi:[0,1,1]
	v_fmac_f32_e32 v8, v124, v61
	s_waitcnt vmcnt(4)
	v_add_u32_e32 v25, s20, v23
	ds_read_b128 v[26:29], v25
	ds_read_b128 v[30:33], v25 offset:8192
	ds_read_b128 v[34:37], v25 offset:16384
	ds_read_b128 v[38:41], v25 offset:24576
	ds_read_b128 v[42:45], v25 offset:32768
	ds_read_b128 v[46:49], v25 offset:40960
	ds_read_b128 v[50:53], v25 offset:49152
	ds_read_b128 v[54:57], v25 offset:57344
	v_add_u32_e32 v25, 0x10000, v25
	ds_read_b128 v[58:61], v25
	s_waitcnt lgkmcnt(6)
	v_mov_b32_e32 v70, v34
	v_mov_b32_e32 v71, v30
	v_mov_b32_e32 v72, v26
	s_waitcnt lgkmcnt(5)
	v_mov_b32_e32 v73, v38
	s_waitcnt lgkmcnt(4)
	v_mov_b32_e32 v74, v42
	s_waitcnt lgkmcnt(3)
	v_mov_b32_e32 v75, v46
	s_waitcnt lgkmcnt(2)
	v_mov_b32_e32 v76, v50
	s_waitcnt lgkmcnt(1)
	v_mov_b32_e32 v77, v54
	v_mov_b32_e32 v30, v35
	v_mov_b32_e32 v38, v27
	v_mov_b32_e32 v46, v43
	v_mov_b32_e32 v54, v51
	v_mov_b32_e32 v26, v36
	v_mov_b32_e32 v27, v32
	v_mov_b32_e32 v34, v28
	v_mov_b32_e32 v35, v40
	v_mov_b32_e32 v42, v44
	v_mov_b32_e32 v43, v48
	v_mov_b32_e32 v50, v52
	v_mov_b32_e32 v51, v56
	s_add_i32 s20, s20, 16
	v_mov_b32_e32 v32, v37
	v_mov_b32_e32 v40, v29
	v_mov_b32_e32 v48, v45
	v_mov_b32_e32 v56, v53
	v_pk_fma_f32 v[12:13], v[126:127], v[70:71], v[12:13] op_sel_hi:[0,1,1]
	v_pk_fma_f32 v[14:15], v[126:127], v[72:73], v[14:15] op_sel_hi:[0,1,1]
	v_pk_fma_f32 v[16:17], v[126:127], v[74:75], v[16:17] op_sel_hi:[0,1,1]
	v_pk_fma_f32 v[18:19], v[126:127], v[76:77], v[18:19] op_sel_hi:[0,1,1]
	s_waitcnt lgkmcnt(0)
	v_fmac_f32_e32 v8, v126, v58
	v_pk_fma_f32 v[12:13], v[128:129], v[30:31], v[12:13] op_sel_hi:[0,1,1]
	v_pk_fma_f32 v[14:15], v[128:129], v[38:39], v[14:15] op_sel_hi:[0,1,1]
	v_pk_fma_f32 v[16:17], v[128:129], v[46:47], v[16:17] op_sel_hi:[0,1,1]
	v_pk_fma_f32 v[18:19], v[128:129], v[54:55], v[18:19] op_sel_hi:[0,1,1]
	v_fmac_f32_e32 v8, v128, v59
	v_pk_fma_f32 v[12:13], v[130:131], v[26:27], v[12:13] op_sel_hi:[0,1,1]
	v_pk_fma_f32 v[14:15], v[130:131], v[34:35], v[14:15] op_sel_hi:[0,1,1]
	v_pk_fma_f32 v[16:17], v[130:131], v[42:43], v[16:17] op_sel_hi:[0,1,1]
	v_pk_fma_f32 v[18:19], v[130:131], v[50:51], v[18:19] op_sel_hi:[0,1,1]
	v_fmac_f32_e32 v8, v130, v60
	v_pk_fma_f32 v[12:13], v[132:133], v[32:33], v[12:13] op_sel_hi:[0,1,1]
	v_pk_fma_f32 v[14:15], v[132:133], v[40:41], v[14:15] op_sel_hi:[0,1,1]
	v_pk_fma_f32 v[16:17], v[132:133], v[48:49], v[16:17] op_sel_hi:[0,1,1]
	v_pk_fma_f32 v[18:19], v[132:133], v[56:57], v[18:19] op_sel_hi:[0,1,1]
	v_fmac_f32_e32 v8, v132, v61
	s_waitcnt vmcnt(0)
	v_add_u32_e32 v25, s20, v23
	ds_read_b128 v[26:29], v25
	ds_read_b128 v[30:33], v25 offset:8192
	ds_read_b128 v[34:37], v25 offset:16384
	ds_read_b128 v[38:41], v25 offset:24576
	ds_read_b128 v[42:45], v25 offset:32768
	ds_read_b128 v[46:49], v25 offset:40960
	ds_read_b128 v[50:53], v25 offset:49152
	ds_read_b128 v[54:57], v25 offset:57344
	v_add_u32_e32 v25, 0x10000, v25
	ds_read_b128 v[58:61], v25
	s_waitcnt lgkmcnt(6)
	v_mov_b32_e32 v70, v34
	v_mov_b32_e32 v71, v30
	v_mov_b32_e32 v72, v26
	s_waitcnt lgkmcnt(5)
	v_mov_b32_e32 v73, v38
	s_waitcnt lgkmcnt(4)
	v_mov_b32_e32 v74, v42
	s_waitcnt lgkmcnt(3)
	v_mov_b32_e32 v75, v46
	s_waitcnt lgkmcnt(2)
	v_mov_b32_e32 v76, v50
	s_waitcnt lgkmcnt(1)
	v_mov_b32_e32 v77, v54
	v_mov_b32_e32 v30, v35
	v_mov_b32_e32 v38, v27
	v_mov_b32_e32 v46, v43
	v_mov_b32_e32 v54, v51
	v_mov_b32_e32 v26, v36
	v_mov_b32_e32 v27, v32
	v_mov_b32_e32 v34, v28
	v_mov_b32_e32 v35, v40
	v_mov_b32_e32 v42, v44
	v_mov_b32_e32 v43, v48
	v_mov_b32_e32 v50, v52
	v_mov_b32_e32 v51, v56
	s_add_i32 s20, s20, 16
	v_mov_b32_e32 v32, v37
	v_mov_b32_e32 v40, v29
	v_mov_b32_e32 v48, v45
	v_mov_b32_e32 v56, v53
	v_pk_fma_f32 v[12:13], v[134:135], v[70:71], v[12:13] op_sel_hi:[0,1,1]
	v_pk_fma_f32 v[14:15], v[134:135], v[72:73], v[14:15] op_sel_hi:[0,1,1]
	v_pk_fma_f32 v[16:17], v[134:135], v[74:75], v[16:17] op_sel_hi:[0,1,1]
	v_pk_fma_f32 v[18:19], v[134:135], v[76:77], v[18:19] op_sel_hi:[0,1,1]
	s_waitcnt lgkmcnt(0)
	v_fmac_f32_e32 v8, v134, v58
	v_pk_fma_f32 v[12:13], v[136:137], v[30:31], v[12:13] op_sel_hi:[0,1,1]
	v_pk_fma_f32 v[14:15], v[136:137], v[38:39], v[14:15] op_sel_hi:[0,1,1]
	v_pk_fma_f32 v[16:17], v[136:137], v[46:47], v[16:17] op_sel_hi:[0,1,1]
	v_pk_fma_f32 v[18:19], v[136:137], v[54:55], v[18:19] op_sel_hi:[0,1,1]
	v_fmac_f32_e32 v8, v136, v59
	v_pk_fma_f32 v[12:13], v[138:139], v[26:27], v[12:13] op_sel_hi:[0,1,1]
	v_pk_fma_f32 v[14:15], v[138:139], v[34:35], v[14:15] op_sel_hi:[0,1,1]
	v_pk_fma_f32 v[16:17], v[138:139], v[42:43], v[16:17] op_sel_hi:[0,1,1]
	v_pk_fma_f32 v[18:19], v[138:139], v[50:51], v[18:19] op_sel_hi:[0,1,1]
	v_fmac_f32_e32 v8, v138, v60
	v_pk_fma_f32 v[12:13], v[140:141], v[32:33], v[12:13] op_sel_hi:[0,1,1]
	v_pk_fma_f32 v[14:15], v[140:141], v[40:41], v[14:15] op_sel_hi:[0,1,1]
	v_pk_fma_f32 v[16:17], v[140:141], v[48:49], v[16:17] op_sel_hi:[0,1,1]
	v_pk_fma_f32 v[18:19], v[140:141], v[56:57], v[18:19] op_sel_hi:[0,1,1]
	v_fmac_f32_e32 v8, v140, v61
	ds_write2st64_b32 v24, v14, v13 offset1:1
	ds_write2st64_b32 v24, v12, v15 offset0:2 offset1:3
	ds_write2st64_b32 v24, v16, v17 offset0:4 offset1:5
	ds_write2st64_b32 v24, v18, v19 offset0:6 offset1:7
	ds_write_b32 v24, v8 offset:2048
	s_waitcnt lgkmcnt(0)
	s_barrier
	s_and_saveexec_b64 s[6:7], s[4:5]
	s_cbranch_execz .LBB0_10
	s_mul_i32 s20, s19, 0x1800
	s_add_i32 s20, s20, s22
	v_or_b32_e32 v10, s20, v20
	v_ashrrev_i32_e32 v11, 31, v10
	s_mul_i32 s19, s19, 9
	v_lshl_add_u64 v[10:11], v[10:11], 2, s[72:73]
	v_or_b32_e32 v8, s22, v20
	s_mov_b64 s[22:23], 0
	v_mov_b32_e32 v12, v2

.LBB0_274:
	s_bfe_u32 s0, s8, 0x30002
	s_lshl_b32 s1, s0, 14
	s_add_i32 s42, s6, s1
	s_and_b32 s1, s7, 0xffffff80
	v_or_b32_e32 v50, s1, v192
	s_lshl_b32 s0, s0, 7
	s_lshl_b32 s1, s8, 5
	v_lshl_add_u64 v[48:49], s[42:43], 1, v[44:45]
	s_add_i32 s42, s5, s0
	s_lshl_b32 s0, s8, 2
	s_and_b32 s9, s1, 0x3e0
	s_and_b32 s0, s0, 0xffffff80
	v_or_b32_e32 v22, s9, v193
	v_or_b32_e32 v2, s0, v67
	v_or_b32_e32 v194, s5, v22
	v_readlane_b32 s52, v252, 12
	v_ashrrev_i32_e32 v3, 31, v2
	v_lshlrev_b64 v[4:5], 2, v[194:195]
	v_readlane_b32 s53, v252, 13
	v_readlane_b32 s54, v252, 14
	v_readlane_b32 s55, v252, 15
	s_ashr_i32 s1, s0, 31
	v_lshl_add_u64 v[2:3], v[2:3], 3, s[2:3]
	v_lshl_add_u64 v[62:63], s[52:53], 0, v[4:5]
	v_lshl_add_u64 v[64:65], s[54:55], 0, v[4:5]
	v_mul_u32_u24_e32 v4, 0x4800, v22
	global_load_dwordx4 v[76:79], v[2:3], off
	global_load_dwordx4 v[80:83], v[2:3], off offset:16
	global_load_dwordx4 v[84:87], v[2:3], off offset:32
	global_load_dwordx4 v[88:91], v[2:3], off offset:48
	global_load_dwordx4 v[92:95], v[2:3], off offset:256
	global_load_dwordx4 v[96:99], v[2:3], off offset:272
	global_load_dwordx4 v[100:103], v[2:3], off offset:288
	global_load_dwordx4 v[104:107], v[2:3], off offset:304
	global_load_dwordx4 v[108:111], v[2:3], off offset:512
	global_load_dwordx4 v[112:115], v[2:3], off offset:528
	global_load_dwordx4 v[116:119], v[2:3], off offset:544
	global_load_dwordx4 v[120:123], v[2:3], off offset:560
	global_load_dwordx4 v[124:127], v[2:3], off offset:768
	global_load_dwordx4 v[128:131], v[2:3], off offset:784
	global_load_dwordx4 v[132:135], v[2:3], off offset:800
	global_load_dwordx4 v[136:139], v[2:3], off offset:816
	v_lshl_add_u64 v[2:3], s[0:1], 1, v[42:43]
	v_lshlrev_b32_e32 v194, 1, v4
	v_lshl_add_u64 v[60:61], v[2:3], 0, v[194:195]
	s_mov_b32 s1, 0x24000
	s_mov_b64 s[10:11], 0x24000
	v_lshl_add_u64 v[54:55], v[60:61], 0, s[10:11]
	v_lshl_add_u64 v[52:53], s[42:43], 2, v[46:47]
	global_load_dwordx4 v[140:143], v[60:61], off
	global_load_dwordx4 v[144:147], v[60:61], off offset:64
	global_load_dwordx4 v[148:151], v[60:61], off offset:128
	global_load_dwordx4 v[152:155], v[60:61], off offset:192
	global_load_dwordx4 v[156:159], v[54:55], off
	global_load_dwordx4 v[160:163], v[54:55], off offset:64
	global_load_dwordx4 v[164:167], v[54:55], off offset:128
	global_load_dwordx4 v[168:171], v[54:55], off offset:192
	global_load_dword v172, v[62:63], off
	global_load_dword v173, v[64:65], off
	global_load_dword v174, v[62:63], off offset:16
	global_load_dword v175, v[64:65], off offset:16
	v_readlane_b32 s56, v252, 16
	v_readlane_b32 s57, v252, 17
	v_readlane_b32 s58, v252, 18
	v_readlane_b32 s59, v252, 19
	v_readlane_b32 s60, v252, 20
	v_readlane_b32 s61, v252, 21
	v_readlane_b32 s62, v252, 22
	v_readlane_b32 s63, v252, 23
	v_readlane_b32 s64, v252, 24
	v_readlane_b32 s65, v252, 25
	v_readlane_b32 s66, v252, 26
	v_readlane_b32 s67, v252, 27
	v_readlane_b32 s0, v251, 35
	v_readlane_b32 s1, v251, 36
	s_waitcnt vmcnt(0)
	v_lshlrev_b32_e32 v34, 16, v140
	v_and_b32_e32 v35, 0xffff0000, v140
	v_sub_f32_e32 v34, v34, v76
	v_sub_f32_e32 v35, v35, v78
	v_mul_f32_e32 v34, v77, v34
	v_mul_f32_e32 v35, v79, v35
	v_fma_f32 v34, v172, v34, v173
	v_fma_f32 v35, v172, v35, v173
	v_cvt_pk_bf16_f32 v2, v34, v35
	v_lshlrev_b32_e32 v34, 16, v141
	v_and_b32_e32 v35, 0xffff0000, v141
	v_sub_f32_e32 v34, v34, v80
	v_sub_f32_e32 v35, v35, v82
	v_mul_f32_e32 v34, v81, v34
	v_mul_f32_e32 v35, v83, v35
	v_fma_f32 v34, v172, v34, v173
	v_fma_f32 v35, v172, v35, v173
	v_cvt_pk_bf16_f32 v3, v34, v35
	v_lshlrev_b32_e32 v34, 16, v142
	v_and_b32_e32 v35, 0xffff0000, v142
	v_sub_f32_e32 v34, v34, v84
	v_sub_f32_e32 v35, v35, v86
	v_mul_f32_e32 v34, v85, v34
	v_mul_f32_e32 v35, v87, v35
	v_fma_f32 v34, v172, v34, v173
	v_fma_f32 v35, v172, v35, v173
	v_cvt_pk_bf16_f32 v4, v34, v35
	v_lshlrev_b32_e32 v34, 16, v143
	v_and_b32_e32 v35, 0xffff0000, v143
	v_sub_f32_e32 v34, v34, v88
	v_sub_f32_e32 v35, v35, v90
	v_mul_f32_e32 v34, v89, v34
	v_mul_f32_e32 v35, v91, v35
	v_fma_f32 v34, v172, v34, v173
	v_fma_f32 v35, v172, v35, v173
	v_cvt_pk_bf16_f32 v5, v34, v35
	v_lshlrev_b32_e32 v34, 16, v156
	v_and_b32_e32 v35, 0xffff0000, v156
	v_sub_f32_e32 v34, v34, v76
	v_sub_f32_e32 v35, v35, v78
	v_mul_f32_e32 v34, v77, v34
	v_mul_f32_e32 v35, v79, v35
	v_fma_f32 v34, v174, v34, v175
	v_fma_f32 v35, v174, v35, v175
	v_cvt_pk_bf16_f32 v6, v34, v35
	v_lshlrev_b32_e32 v34, 16, v157
	v_and_b32_e32 v35, 0xffff0000, v157
	v_sub_f32_e32 v34, v34, v80
	v_sub_f32_e32 v35, v35, v82
	v_mul_f32_e32 v34, v81, v34
	v_mul_f32_e32 v35, v83, v35
	v_fma_f32 v34, v174, v34, v175
	v_fma_f32 v35, v174, v35, v175
	v_cvt_pk_bf16_f32 v7, v34, v35
	v_lshlrev_b32_e32 v34, 16, v158
	v_and_b32_e32 v35, 0xffff0000, v158
	v_sub_f32_e32 v34, v34, v84
	v_sub_f32_e32 v35, v35, v86
	v_mul_f32_e32 v34, v85, v34
	v_mul_f32_e32 v35, v87, v35
	v_fma_f32 v34, v174, v34, v175
	v_fma_f32 v35, v174, v35, v175
	v_cvt_pk_bf16_f32 v8, v34, v35
	v_lshlrev_b32_e32 v34, 16, v159
	v_and_b32_e32 v35, 0xffff0000, v159
	v_sub_f32_e32 v34, v34, v88
	v_sub_f32_e32 v35, v35, v90
	v_mul_f32_e32 v34, v89, v34
	v_mul_f32_e32 v35, v91, v35
	v_fma_f32 v34, v174, v34, v175
	v_fma_f32 v35, v174, v35, v175
	v_cvt_pk_bf16_f32 v9, v34, v35
	v_lshlrev_b32_e32 v34, 16, v144
	v_and_b32_e32 v35, 0xffff0000, v144
	v_sub_f32_e32 v34, v34, v92
	v_sub_f32_e32 v35, v35, v94
	v_mul_f32_e32 v34, v93, v34
	v_mul_f32_e32 v35, v95, v35
	v_fma_f32 v34, v172, v34, v173
	v_fma_f32 v35, v172, v35, v173
	v_cvt_pk_bf16_f32 v10, v34, v35
	v_lshlrev_b32_e32 v34, 16, v145
	v_and_b32_e32 v35, 0xffff0000, v145
	v_sub_f32_e32 v34, v34, v96
	v_sub_f32_e32 v35, v35, v98
	v_mul_f32_e32 v34, v97, v34
	v_mul_f32_e32 v35, v99, v35
	v_fma_f32 v34, v172, v34, v173
	v_fma_f32 v35, v172, v35, v173
	v_cvt_pk_bf16_f32 v11, v34, v35
	v_lshlrev_b32_e32 v34, 16, v146
	v_and_b32_e32 v35, 0xffff0000, v146
	v_sub_f32_e32 v34, v34, v100
	v_sub_f32_e32 v35, v35, v102
	v_mul_f32_e32 v34, v101, v34
	v_mul_f32_e32 v35, v103, v35
	v_fma_f32 v34, v172, v34, v173
	v_fma_f32 v35, v172, v35, v173
	v_cvt_pk_bf16_f32 v12, v34, v35
	v_lshlrev_b32_e32 v34, 16, v147
	v_and_b32_e32 v35, 0xffff0000, v147
	v_sub_f32_e32 v34, v34, v104
	v_sub_f32_e32 v35, v35, v106
	v_mul_f32_e32 v34, v105, v34
	v_mul_f32_e32 v35, v107, v35
	v_fma_f32 v34, v172, v34, v173
	v_fma_f32 v35, v172, v35, v173
	v_cvt_pk_bf16_f32 v13, v34, v35
	v_lshlrev_b32_e32 v34, 16, v160
	v_and_b32_e32 v35, 0xffff0000, v160
	v_sub_f32_e32 v34, v34, v92
	v_sub_f32_e32 v35, v35, v94
	v_mul_f32_e32 v34, v93, v34
	v_mul_f32_e32 v35, v95, v35
	v_fma_f32 v34, v174, v34, v175
	v_fma_f32 v35, v174, v35, v175
	v_cvt_pk_bf16_f32 v14, v34, v35
	v_lshlrev_b32_e32 v34, 16, v161
	v_and_b32_e32 v35, 0xffff0000, v161
	v_sub_f32_e32 v34, v34, v96
	v_sub_f32_e32 v35, v35, v98
	v_mul_f32_e32 v34, v97, v34
	v_mul_f32_e32 v35, v99, v35
	v_fma_f32 v34, v174, v34, v175
	v_fma_f32 v35, v174, v35, v175
	v_cvt_pk_bf16_f32 v15, v34, v35
	v_lshlrev_b32_e32 v34, 16, v162
	v_and_b32_e32 v35, 0xffff0000, v162
	v_sub_f32_e32 v34, v34, v100
	v_sub_f32_e32 v35, v35, v102
	v_mul_f32_e32 v34, v101, v34
	v_mul_f32_e32 v35, v103, v35
	v_fma_f32 v34, v174, v34, v175
	v_fma_f32 v35, v174, v35, v175
	v_cvt_pk_bf16_f32 v16, v34, v35
	v_lshlrev_b32_e32 v34, 16, v163
	v_and_b32_e32 v35, 0xffff0000, v163
	v_sub_f32_e32 v34, v34, v104
	v_sub_f32_e32 v35, v35, v106
	v_mul_f32_e32 v34, v105, v34
	v_mul_f32_e32 v35, v107, v35
	v_fma_f32 v34, v174, v34, v175
	v_fma_f32 v35, v174, v35, v175
	v_cvt_pk_bf16_f32 v17, v34, v35
	v_lshlrev_b32_e32 v34, 16, v148
	v_and_b32_e32 v35, 0xffff0000, v148
	v_sub_f32_e32 v34, v34, v108
	v_sub_f32_e32 v35, v35, v110
	v_mul_f32_e32 v34, v109, v34
	v_mul_f32_e32 v35, v111, v35
	v_fma_f32 v34, v172, v34, v173
	v_fma_f32 v35, v172, v35, v173
	v_cvt_pk_bf16_f32 v18, v34, v35
	v_lshlrev_b32_e32 v34, 16, v149
	v_and_b32_e32 v35, 0xffff0000, v149
	v_sub_f32_e32 v34, v34, v112
	v_sub_f32_e32 v35, v35, v114
	v_mul_f32_e32 v34, v113, v34
	v_mul_f32_e32 v35, v115, v35
	v_fma_f32 v34, v172, v34, v173
	v_fma_f32 v35, v172, v35, v173
	v_cvt_pk_bf16_f32 v19, v34, v35
	v_lshlrev_b32_e32 v34, 16, v150
	v_and_b32_e32 v35, 0xffff0000, v150
	v_sub_f32_e32 v34, v34, v116
	v_sub_f32_e32 v35, v35, v118
	v_mul_f32_e32 v34, v117, v34
	v_mul_f32_e32 v35, v119, v35
	v_fma_f32 v34, v172, v34, v173
	v_fma_f32 v35, v172, v35, v173
	v_cvt_pk_bf16_f32 v20, v34, v35
	v_lshlrev_b32_e32 v34, 16, v151
	v_and_b32_e32 v35, 0xffff0000, v151
	v_sub_f32_e32 v34, v34, v120
	v_sub_f32_e32 v35, v35, v122
	v_mul_f32_e32 v34, v121, v34
	v_mul_f32_e32 v35, v123, v35
	v_fma_f32 v34, v172, v34, v173
	v_fma_f32 v35, v172, v35, v173
	v_cvt_pk_bf16_f32 v21, v34, v35
	v_lshlrev_b32_e32 v34, 16, v164
	v_and_b32_e32 v35, 0xffff0000, v164
	v_sub_f32_e32 v34, v34, v108
	v_sub_f32_e32 v35, v35, v110
	v_mul_f32_e32 v34, v109, v34
	v_mul_f32_e32 v35, v111, v35
	v_fma_f32 v34, v174, v34, v175
	v_fma_f32 v35, v174, v35, v175
	v_cvt_pk_bf16_f32 v22, v34, v35
	v_lshlrev_b32_e32 v34, 16, v165
	v_and_b32_e32 v35, 0xffff0000, v165
	v_sub_f32_e32 v34, v34, v112
	v_sub_f32_e32 v35, v35, v114
	v_mul_f32_e32 v34, v113, v34
	v_mul_f32_e32 v35, v115, v35
	v_fma_f32 v34, v174, v34, v175
	v_fma_f32 v35, v174, v35, v175
	v_cvt_pk_bf16_f32 v23, v34, v35
	v_lshlrev_b32_e32 v34, 16, v166
	v_and_b32_e32 v35, 0xffff0000, v166
	v_sub_f32_e32 v34, v34, v116
	v_sub_f32_e32 v35, v35, v118
	v_mul_f32_e32 v34, v117, v34
	v_mul_f32_e32 v35, v119, v35
	v_fma_f32 v34, v174, v34, v175
	v_fma_f32 v35, v174, v35, v175
	v_cvt_pk_bf16_f32 v24, v34, v35
	v_lshlrev_b32_e32 v34, 16, v167
	v_and_b32_e32 v35, 0xffff0000, v167
	v_sub_f32_e32 v34, v34, v120
	v_sub_f32_e32 v35, v35, v122
	v_mul_f32_e32 v34, v121, v34
	v_mul_f32_e32 v35, v123, v35
	v_fma_f32 v34, v174, v34, v175
	v_fma_f32 v35, v174, v35, v175
	v_cvt_pk_bf16_f32 v25, v34, v35
	v_lshlrev_b32_e32 v34, 16, v152
	v_and_b32_e32 v35, 0xffff0000, v152
	v_sub_f32_e32 v34, v34, v124
	v_sub_f32_e32 v35, v35, v126
	v_mul_f32_e32 v34, v125, v34
	v_mul_f32_e32 v35, v127, v35
	v_fma_f32 v34, v172, v34, v173
	v_fma_f32 v35, v172, v35, v173
	v_cvt_pk_bf16_f32 v26, v34, v35
	v_lshlrev_b32_e32 v34, 16, v153
	v_and_b32_e32 v35, 0xffff0000, v153
	v_sub_f32_e32 v34, v34, v128
	v_sub_f32_e32 v35, v35, v130
	v_mul_f32_e32 v34, v129, v34
	v_mul_f32_e32 v35, v131, v35
	v_fma_f32 v34, v172, v34, v173
	v_fma_f32 v35, v172, v35, v173
	v_cvt_pk_bf16_f32 v27, v34, v35
	v_lshlrev_b32_e32 v34, 16, v154
	v_and_b32_e32 v35, 0xffff0000, v154
	v_sub_f32_e32 v34, v34, v132
	v_sub_f32_e32 v35, v35, v134
	v_mul_f32_e32 v34, v133, v34
	v_mul_f32_e32 v35, v135, v35
	v_fma_f32 v34, v172, v34, v173
	v_fma_f32 v35, v172, v35, v173
	v_cvt_pk_bf16_f32 v28, v34, v35
	v_lshlrev_b32_e32 v34, 16, v155
	v_and_b32_e32 v35, 0xffff0000, v155
	v_sub_f32_e32 v34, v34, v136
	v_sub_f32_e32 v35, v35, v138
	v_mul_f32_e32 v34, v137, v34
	v_mul_f32_e32 v35, v139, v35
	v_fma_f32 v34, v172, v34, v173
	v_fma_f32 v35, v172, v35, v173
	v_cvt_pk_bf16_f32 v29, v34, v35
	v_lshlrev_b32_e32 v34, 16, v168
	v_and_b32_e32 v35, 0xffff0000, v168
	v_sub_f32_e32 v34, v34, v124
	v_sub_f32_e32 v35, v35, v126
	v_mul_f32_e32 v34, v125, v34
	v_mul_f32_e32 v35, v127, v35
	v_fma_f32 v34, v174, v34, v175
	v_fma_f32 v35, v174, v35, v175
	v_cvt_pk_bf16_f32 v30, v34, v35
	v_lshlrev_b32_e32 v34, 16, v169
	v_and_b32_e32 v35, 0xffff0000, v169
	v_sub_f32_e32 v34, v34, v128
	v_sub_f32_e32 v35, v35, v130
	v_mul_f32_e32 v34, v129, v34
	v_mul_f32_e32 v35, v131, v35
	v_fma_f32 v34, v174, v34, v175
	v_fma_f32 v35, v174, v35, v175
	v_cvt_pk_bf16_f32 v31, v34, v35
	v_lshlrev_b32_e32 v34, 16, v170
	v_and_b32_e32 v35, 0xffff0000, v170
	v_sub_f32_e32 v34, v34, v132
	v_sub_f32_e32 v35, v35, v134
	v_mul_f32_e32 v34, v133, v34
	v_mul_f32_e32 v35, v135, v35
	v_fma_f32 v34, v174, v34, v175
	v_fma_f32 v35, v174, v35, v175
	v_cvt_pk_bf16_f32 v32, v34, v35
	v_lshlrev_b32_e32 v34, 16, v171
	v_and_b32_e32 v35, 0xffff0000, v171
	v_sub_f32_e32 v34, v34, v136
	v_sub_f32_e32 v35, v35, v138
	v_mul_f32_e32 v34, v137, v34
	v_mul_f32_e32 v35, v139, v35
	v_fma_f32 v34, v174, v34, v175
	v_fma_f32 v35, v174, v35, v175
	v_cvt_pk_bf16_f32 v33, v34, v35
	v_or_b32_e32 v34, s9, v67
	v_lshlrev_b32_e32 v194, 1, v34
	v_lshl_add_u64 v[54:55], s[0:1], 0, v[194:195]
	v_lshl_add_u64 v[56:57], s[50:51], 0, v[194:195]
	v_add_co_u32_e32 v72, vcc, 0x6400000, v48
	s_nop 1
	v_addc_co_u32_e32 v73, vcc, 0, v49, vcc
	global_load_dwordx4 v[76:79], v[72:73], off
	global_load_dwordx4 v[80:83], v[72:73], off offset:64
	global_load_dwordx4 v[84:87], v[72:73], off offset:128
	global_load_dwordx4 v[88:91], v[72:73], off offset:192
	global_load_dword v172, v[52:53], off offset:-64
	v_mov_b32_e32 v180, v50
	v_mad_i64_i32 v[176:177], s[10:11], v180, s37, v[56:57]
	global_load_dwordx4 v[140:143], v[176:177], off
	global_load_dwordx4 v[156:159], v[176:177], off offset:2048
	v_add_co_u32_e32 v72, vcc, 0x1000, v72
	s_nop 1
	v_addc_co_u32_e32 v73, vcc, 0, v73, vcc
	global_load_dwordx4 v[92:95], v[72:73], off
	global_load_dwordx4 v[96:99], v[72:73], off offset:64
	global_load_dwordx4 v[100:103], v[72:73], off offset:128
	global_load_dwordx4 v[104:107], v[72:73], off offset:192
	global_load_dword v173, v[52:53], off offset:0
	v_add_u32_e32 v180, 16, v50
	v_mad_i64_i32 v[176:177], s[10:11], v180, s37, v[56:57]
	global_load_dwordx4 v[144:147], v[176:177], off
	global_load_dwordx4 v[160:163], v[176:177], off offset:2048
	v_add_co_u32_e32 v72, vcc, 0x1000, v72
	s_nop 1
	v_addc_co_u32_e32 v73, vcc, 0, v73, vcc
	global_load_dwordx4 v[108:111], v[72:73], off
	global_load_dwordx4 v[112:115], v[72:73], off offset:64
	global_load_dwordx4 v[116:119], v[72:73], off offset:128
	global_load_dwordx4 v[120:123], v[72:73], off offset:192
	global_load_dword v174, v[52:53], off offset:64
	v_add_u32_e32 v180, 32, v50
	v_mad_i64_i32 v[176:177], s[10:11], v180, s37, v[56:57]
	global_load_dwordx4 v[148:151], v[176:177], off
	global_load_dwordx4 v[164:167], v[176:177], off offset:2048
	v_add_co_u32_e32 v72, vcc, 0x1000, v72
	s_nop 1
	v_addc_co_u32_e32 v73, vcc, 0, v73, vcc
	global_load_dwordx4 v[124:127], v[72:73], off
	global_load_dwordx4 v[128:131], v[72:73], off offset:64
	global_load_dwordx4 v[132:135], v[72:73], off offset:128
	global_load_dwordx4 v[136:139], v[72:73], off offset:192
	global_load_dword v175, v[52:53], off offset:128
	v_add_u32_e32 v180, 48, v50
	v_mad_i64_i32 v[176:177], s[10:11], v180, s37, v[56:57]
	global_load_dwordx4 v[152:155], v[176:177], off
	global_load_dwordx4 v[168:171], v[176:177], off offset:2048
	v_add_co_u32_e32 v72, vcc, 0x1000, v72
	s_nop 1
	v_addc_co_u32_e32 v73, vcc, 0, v73, vcc
	s_waitcnt vmcnt(21)
	v_mfma_f32_16x16x32_bf16 v[38:41], v[2:5], v[76:79], 0
	v_mfma_f32_16x16x32_bf16 v[34:37], v[6:9], v[76:79], 0
	v_mfma_f32_16x16x32_bf16 v[38:41], v[10:13], v[80:83], v[38:41]
	v_mfma_f32_16x16x32_bf16 v[34:37], v[14:17], v[80:83], v[34:37]
	v_mfma_f32_16x16x32_bf16 v[38:41], v[18:21], v[84:87], v[38:41]
	v_mfma_f32_16x16x32_bf16 v[34:37], v[22:25], v[84:87], v[34:37]
	v_mfma_f32_16x16x32_bf16 v[38:41], v[26:29], v[88:91], v[38:41]
	v_mfma_f32_16x16x32_bf16 v[34:37], v[30:33], v[88:91], v[34:37]
	v_mov_b32_e32 v180, v50
	v_ashrrev_i32_e32 v181, 31, v180
	v_lshlrev_b64 v[178:179], 11, v[180:181]
	v_lshl_add_u64 v[178:179], v[54:55], 0, v[178:179]
	s_nop 7
	v_add_f32_e32 v62, v38, v172
	v_add_f32_e32 v63, v39, v172
	v_lshlrev_b32_e32 v64, 16, v140
	v_and_b32_e32 v65, 0xffff0000, v140
	v_mul_f32_e32 v62, v62, v64
	v_mul_f32_e32 v63, v63, v65
	v_lshlrev_b32_e32 v64, 16, v156
	v_and_b32_e32 v65, 0xffff0000, v156
	v_mul_f32_e32 v62, v62, v64
	v_mul_f32_e32 v63, v63, v65
	v_cvt_pk_bf16_f32 v58, v62, v63
	v_add_f32_e32 v62, v40, v172
	v_add_f32_e32 v63, v41, v172
	v_lshlrev_b32_e32 v64, 16, v141
	v_and_b32_e32 v65, 0xffff0000, v141
	v_mul_f32_e32 v62, v62, v64
	v_mul_f32_e32 v63, v63, v65
	v_lshlrev_b32_e32 v64, 16, v157
	v_and_b32_e32 v65, 0xffff0000, v157
	v_mul_f32_e32 v62, v62, v64
	v_mul_f32_e32 v63, v63, v65
	v_cvt_pk_bf16_f32 v59, v62, v63
	v_add_f32_e32 v62, v34, v172
	v_add_f32_e32 v63, v35, v172
	v_lshlrev_b32_e32 v64, 16, v142
	v_and_b32_e32 v65, 0xffff0000, v142
	v_mul_f32_e32 v62, v62, v64
	v_mul_f32_e32 v63, v63, v65
	v_lshlrev_b32_e32 v64, 16, v158
	v_and_b32_e32 v65, 0xffff0000, v158
	v_mul_f32_e32 v62, v62, v64
	v_mul_f32_e32 v63, v63, v65
	v_cvt_pk_bf16_f32 v60, v62, v63
	v_add_f32_e32 v62, v36, v172
	v_add_f32_e32 v63, v37, v172
	v_lshlrev_b32_e32 v64, 16, v143
	v_and_b32_e32 v65, 0xffff0000, v143
	v_mul_f32_e32 v62, v62, v64
	v_mul_f32_e32 v63, v63, v65
	v_lshlrev_b32_e32 v64, 16, v159
	v_and_b32_e32 v65, 0xffff0000, v159
	v_mul_f32_e32 v62, v62, v64
	v_mul_f32_e32 v63, v63, v65
	v_cvt_pk_bf16_f32 v61, v62, v63
	global_store_dwordx4 v[178:179], v[58:61], off
	s_waitcnt vmcnt(14)
	v_mfma_f32_16x16x32_bf16 v[38:41], v[2:5], v[92:95], 0
	v_mfma_f32_16x16x32_bf16 v[34:37], v[6:9], v[92:95], 0
	v_mfma_f32_16x16x32_bf16 v[38:41], v[10:13], v[96:99], v[38:41]
	v_mfma_f32_16x16x32_bf16 v[34:37], v[14:17], v[96:99], v[34:37]
	v_mfma_f32_16x16x32_bf16 v[38:41], v[18:21], v[100:103], v[38:41]
	v_mfma_f32_16x16x32_bf16 v[34:37], v[22:25], v[100:103], v[34:37]
	v_mfma_f32_16x16x32_bf16 v[38:41], v[26:29], v[104:107], v[38:41]
	v_mfma_f32_16x16x32_bf16 v[34:37], v[30:33], v[104:107], v[34:37]
	v_add_u32_e32 v180, 16, v50
	v_ashrrev_i32_e32 v181, 31, v180
	v_lshlrev_b64 v[178:179], 11, v[180:181]
	v_lshl_add_u64 v[178:179], v[54:55], 0, v[178:179]
	s_nop 7
	v_add_f32_e32 v62, v38, v173
	v_add_f32_e32 v63, v39, v173
	v_lshlrev_b32_e32 v64, 16, v144
	v_and_b32_e32 v65, 0xffff0000, v144
	v_mul_f32_e32 v62, v62, v64
	v_mul_f32_e32 v63, v63, v65
	v_lshlrev_b32_e32 v64, 16, v160
	v_and_b32_e32 v65, 0xffff0000, v160
	v_mul_f32_e32 v62, v62, v64
	v_mul_f32_e32 v63, v63, v65
	v_cvt_pk_bf16_f32 v58, v62, v63
	v_add_f32_e32 v62, v40, v173
	v_add_f32_e32 v63, v41, v173
	v_lshlrev_b32_e32 v64, 16, v145
	v_and_b32_e32 v65, 0xffff0000, v145
	v_mul_f32_e32 v62, v62, v64
	v_mul_f32_e32 v63, v63, v65
	v_lshlrev_b32_e32 v64, 16, v161
	v_and_b32_e32 v65, 0xffff0000, v161
	v_mul_f32_e32 v62, v62, v64
	v_mul_f32_e32 v63, v63, v65
	v_cvt_pk_bf16_f32 v59, v62, v63
	v_add_f32_e32 v62, v34, v173
	v_add_f32_e32 v63, v35, v173
	v_lshlrev_b32_e32 v64, 16, v146
	v_and_b32_e32 v65, 0xffff0000, v146
	v_mul_f32_e32 v62, v62, v64
	v_mul_f32_e32 v63, v63, v65
	v_lshlrev_b32_e32 v64, 16, v162
	v_and_b32_e32 v65, 0xffff0000, v162
	v_mul_f32_e32 v62, v62, v64
	v_mul_f32_e32 v63, v63, v65
	v_cvt_pk_bf16_f32 v60, v62, v63
	v_add_f32_e32 v62, v36, v173
	v_add_f32_e32 v63, v37, v173
	v_lshlrev_b32_e32 v64, 16, v147
	v_and_b32_e32 v65, 0xffff0000, v147
	v_mul_f32_e32 v62, v62, v64
	v_mul_f32_e32 v63, v63, v65
	v_lshlrev_b32_e32 v64, 16, v163
	v_and_b32_e32 v65, 0xffff0000, v163
	v_mul_f32_e32 v62, v62, v64
	v_mul_f32_e32 v63, v63, v65
	v_cvt_pk_bf16_f32 v61, v62, v63
	global_store_dwordx4 v[178:179], v[58:61], off
	s_waitcnt vmcnt(7)
	v_mfma_f32_16x16x32_bf16 v[38:41], v[2:5], v[108:111], 0
	v_mfma_f32_16x16x32_bf16 v[34:37], v[6:9], v[108:111], 0
	v_mfma_f32_16x16x32_bf16 v[38:41], v[10:13], v[112:115], v[38:41]
	v_mfma_f32_16x16x32_bf16 v[34:37], v[14:17], v[112:115], v[34:37]
	v_mfma_f32_16x16x32_bf16 v[38:41], v[18:21], v[116:119], v[38:41]
	v_mfma_f32_16x16x32_bf16 v[34:37], v[22:25], v[116:119], v[34:37]
	v_mfma_f32_16x16x32_bf16 v[38:41], v[26:29], v[120:123], v[38:41]
	v_mfma_f32_16x16x32_bf16 v[34:37], v[30:33], v[120:123], v[34:37]
	v_add_u32_e32 v180, 32, v50
	v_ashrrev_i32_e32 v181, 31, v180
	v_lshlrev_b64 v[178:179], 11, v[180:181]
	v_lshl_add_u64 v[178:179], v[54:55], 0, v[178:179]
	s_nop 7
	v_add_f32_e32 v62, v38, v174
	v_add_f32_e32 v63, v39, v174
	v_lshlrev_b32_e32 v64, 16, v148
	v_and_b32_e32 v65, 0xffff0000, v148
	v_mul_f32_e32 v62, v62, v64
	v_mul_f32_e32 v63, v63, v65
	v_lshlrev_b32_e32 v64, 16, v164
	v_and_b32_e32 v65, 0xffff0000, v164
	v_mul_f32_e32 v62, v62, v64
	v_mul_f32_e32 v63, v63, v65
	v_cvt_pk_bf16_f32 v58, v62, v63
	v_add_f32_e32 v62, v40, v174
	v_add_f32_e32 v63, v41, v174
	v_lshlrev_b32_e32 v64, 16, v149
	v_and_b32_e32 v65, 0xffff0000, v149
	v_mul_f32_e32 v62, v62, v64
	v_mul_f32_e32 v63, v63, v65
	v_lshlrev_b32_e32 v64, 16, v165
	v_and_b32_e32 v65, 0xffff0000, v165
	v_mul_f32_e32 v62, v62, v64
	v_mul_f32_e32 v63, v63, v65
	v_cvt_pk_bf16_f32 v59, v62, v63
	v_add_f32_e32 v62, v34, v174
	v_add_f32_e32 v63, v35, v174
	v_lshlrev_b32_e32 v64, 16, v150
	v_and_b32_e32 v65, 0xffff0000, v150
	v_mul_f32_e32 v62, v62, v64
	v_mul_f32_e32 v63, v63, v65
	v_lshlrev_b32_e32 v64, 16, v166
	v_and_b32_e32 v65, 0xffff0000, v166
	v_mul_f32_e32 v62, v62, v64
	v_mul_f32_e32 v63, v63, v65
	v_cvt_pk_bf16_f32 v60, v62, v63
	v_add_f32_e32 v62, v36, v174
	v_add_f32_e32 v63, v37, v174
	v_lshlrev_b32_e32 v64, 16, v151
	v_and_b32_e32 v65, 0xffff0000, v151
	v_mul_f32_e32 v62, v62, v64
	v_mul_f32_e32 v63, v63, v65
	v_lshlrev_b32_e32 v64, 16, v167
	v_and_b32_e32 v65, 0xffff0000, v167
	v_mul_f32_e32 v62, v62, v64
	v_mul_f32_e32 v63, v63, v65
	v_cvt_pk_bf16_f32 v61, v62, v63
	global_store_dwordx4 v[178:179], v[58:61], off
	s_waitcnt vmcnt(0)
	v_mfma_f32_16x16x32_bf16 v[38:41], v[2:5], v[124:127], 0
	v_mfma_f32_16x16x32_bf16 v[34:37], v[6:9], v[124:127], 0
	v_mfma_f32_16x16x32_bf16 v[38:41], v[10:13], v[128:131], v[38:41]
	v_mfma_f32_16x16x32_bf16 v[34:37], v[14:17], v[128:131], v[34:37]
	v_mfma_f32_16x16x32_bf16 v[38:41], v[18:21], v[132:135], v[38:41]
	v_mfma_f32_16x16x32_bf16 v[34:37], v[22:25], v[132:135], v[34:37]
	v_mfma_f32_16x16x32_bf16 v[38:41], v[26:29], v[136:139], v[38:41]
	v_mfma_f32_16x16x32_bf16 v[34:37], v[30:33], v[136:139], v[34:37]
	v_add_u32_e32 v180, 48, v50
	v_ashrrev_i32_e32 v181, 31, v180
	v_lshlrev_b64 v[178:179], 11, v[180:181]
	v_lshl_add_u64 v[178:179], v[54:55], 0, v[178:179]
	s_nop 7
	v_add_f32_e32 v62, v38, v175
	v_add_f32_e32 v63, v39, v175
	v_lshlrev_b32_e32 v64, 16, v152
	v_and_b32_e32 v65, 0xffff0000, v152
	v_mul_f32_e32 v62, v62, v64
	v_mul_f32_e32 v63, v63, v65
	v_lshlrev_b32_e32 v64, 16, v168
	v_and_b32_e32 v65, 0xffff0000, v168
	v_mul_f32_e32 v62, v62, v64
	v_mul_f32_e32 v63, v63, v65
	v_cvt_pk_bf16_f32 v58, v62, v63
	v_add_f32_e32 v62, v40, v175
	v_add_f32_e32 v63, v41, v175
	v_lshlrev_b32_e32 v64, 16, v153
	v_and_b32_e32 v65, 0xffff0000, v153
	v_mul_f32_e32 v62, v62, v64
	v_mul_f32_e32 v63, v63, v65
	v_lshlrev_b32_e32 v64, 16, v169
	v_and_b32_e32 v65, 0xffff0000, v169
	v_mul_f32_e32 v62, v62, v64
	v_mul_f32_e32 v63, v63, v65
	v_cvt_pk_bf16_f32 v59, v62, v63
	v_add_f32_e32 v62, v34, v175
	v_add_f32_e32 v63, v35, v175
	v_lshlrev_b32_e32 v64, 16, v154
	v_and_b32_e32 v65, 0xffff0000, v154
	v_mul_f32_e32 v62, v62, v64
	v_mul_f32_e32 v63, v63, v65
	v_lshlrev_b32_e32 v64, 16, v170
	v_and_b32_e32 v65, 0xffff0000, v170
	v_mul_f32_e32 v62, v62, v64
	v_mul_f32_e32 v63, v63, v65
	v_cvt_pk_bf16_f32 v60, v62, v63
	v_add_f32_e32 v62, v36, v175
	v_add_f32_e32 v63, v37, v175
	v_lshlrev_b32_e32 v64, 16, v155
	v_and_b32_e32 v65, 0xffff0000, v155
	v_mul_f32_e32 v62, v62, v64
	v_mul_f32_e32 v63, v63, v65
	v_lshlrev_b32_e32 v64, 16, v171
	v_and_b32_e32 v65, 0xffff0000, v171
	v_mul_f32_e32 v62, v62, v64
	v_mul_f32_e32 v63, v63, v65
	v_cvt_pk_bf16_f32 v61, v62, v63
	global_store_dwordx4 v[178:179], v[58:61], off
	global_load_dwordx4 v[76:79], v[72:73], off
	global_load_dwordx4 v[80:83], v[72:73], off offset:64
	global_load_dwordx4 v[84:87], v[72:73], off offset:128
	global_load_dwordx4 v[88:91], v[72:73], off offset:192
	global_load_dword v172, v[52:53], off offset:192
	v_add_u32_e32 v180, 64, v50
	v_mad_i64_i32 v[176:177], s[10:11], v180, s37, v[56:57]
	global_load_dwordx4 v[140:143], v[176:177], off
	global_load_dwordx4 v[156:159], v[176:177], off offset:2048
	v_add_co_u32_e32 v72, vcc, 0x1000, v72
	s_nop 1
	v_addc_co_u32_e32 v73, vcc, 0, v73, vcc
	global_load_dwordx4 v[92:95], v[72:73], off
	global_load_dwordx4 v[96:99], v[72:73], off offset:64
	global_load_dwordx4 v[100:103], v[72:73], off offset:128
	global_load_dwordx4 v[104:107], v[72:73], off offset:192
	global_load_dword v173, v[52:53], off offset:256
	v_add_u32_e32 v180, 80, v50
	v_mad_i64_i32 v[176:177], s[10:11], v180, s37, v[56:57]
	global_load_dwordx4 v[144:147], v[176:177], off
	global_load_dwordx4 v[160:163], v[176:177], off offset:2048
	v_add_co_u32_e32 v72, vcc, 0x1000, v72
	s_nop 1
	v_addc_co_u32_e32 v73, vcc, 0, v73, vcc
	global_load_dwordx4 v[108:111], v[72:73], off
	global_load_dwordx4 v[112:115], v[72:73], off offset:64
	global_load_dwordx4 v[116:119], v[72:73], off offset:128
	global_load_dwordx4 v[120:123], v[72:73], off offset:192
	global_load_dword v174, v[52:53], off offset:320
	v_add_u32_e32 v180, 96, v50
	v_mad_i64_i32 v[176:177], s[10:11], v180, s37, v[56:57]
	global_load_dwordx4 v[148:151], v[176:177], off
	global_load_dwordx4 v[164:167], v[176:177], off offset:2048
	v_add_co_u32_e32 v72, vcc, 0x1000, v72
	s_nop 1
	v_addc_co_u32_e32 v73, vcc, 0, v73, vcc
	global_load_dwordx4 v[124:127], v[72:73], off
	global_load_dwordx4 v[128:131], v[72:73], off offset:64
	global_load_dwordx4 v[132:135], v[72:73], off offset:128
	global_load_dwordx4 v[136:139], v[72:73], off offset:192
	global_load_dword v175, v[52:53], off offset:384
	v_add_u32_e32 v180, 112, v50
	v_mad_i64_i32 v[176:177], s[10:11], v180, s37, v[56:57]
	global_load_dwordx4 v[152:155], v[176:177], off
	global_load_dwordx4 v[168:171], v[176:177], off offset:2048
	v_add_co_u32_e32 v72, vcc, 0x1000, v72
	s_nop 1
	v_addc_co_u32_e32 v73, vcc, 0, v73, vcc
	s_waitcnt vmcnt(21)
	v_mfma_f32_16x16x32_bf16 v[38:41], v[2:5], v[76:79], 0
	v_mfma_f32_16x16x32_bf16 v[34:37], v[6:9], v[76:79], 0
	v_mfma_f32_16x16x32_bf16 v[38:41], v[10:13], v[80:83], v[38:41]
	v_mfma_f32_16x16x32_bf16 v[34:37], v[14:17], v[80:83], v[34:37]
	v_mfma_f32_16x16x32_bf16 v[38:41], v[18:21], v[84:87], v[38:41]
	v_mfma_f32_16x16x32_bf16 v[34:37], v[22:25], v[84:87], v[34:37]
	v_mfma_f32_16x16x32_bf16 v[38:41], v[26:29], v[88:91], v[38:41]
	v_mfma_f32_16x16x32_bf16 v[34:37], v[30:33], v[88:91], v[34:37]
	v_add_u32_e32 v180, 64, v50
	v_ashrrev_i32_e32 v181, 31, v180
	v_lshlrev_b64 v[178:179], 11, v[180:181]
	v_lshl_add_u64 v[178:179], v[54:55], 0, v[178:179]
	s_nop 7
	v_add_f32_e32 v62, v38, v172
	v_add_f32_e32 v63, v39, v172
	v_lshlrev_b32_e32 v64, 16, v140
	v_and_b32_e32 v65, 0xffff0000, v140
	v_mul_f32_e32 v62, v62, v64
	v_mul_f32_e32 v63, v63, v65
	v_lshlrev_b32_e32 v64, 16, v156
	v_and_b32_e32 v65, 0xffff0000, v156
	v_mul_f32_e32 v62, v62, v64
	v_mul_f32_e32 v63, v63, v65
	v_cvt_pk_bf16_f32 v58, v62, v63
	v_add_f32_e32 v62, v40, v172
	v_add_f32_e32 v63, v41, v172
	v_lshlrev_b32_e32 v64, 16, v141
	v_and_b32_e32 v65, 0xffff0000, v141
	v_mul_f32_e32 v62, v62, v64
	v_mul_f32_e32 v63, v63, v65
	v_lshlrev_b32_e32 v64, 16, v157
	v_and_b32_e32 v65, 0xffff0000, v157
	v_mul_f32_e32 v62, v62, v64
	v_mul_f32_e32 v63, v63, v65
	v_cvt_pk_bf16_f32 v59, v62, v63
	v_add_f32_e32 v62, v34, v172
	v_add_f32_e32 v63, v35, v172
	v_lshlrev_b32_e32 v64, 16, v142
	v_and_b32_e32 v65, 0xffff0000, v142
	v_mul_f32_e32 v62, v62, v64
	v_mul_f32_e32 v63, v63, v65
	v_lshlrev_b32_e32 v64, 16, v158
	v_and_b32_e32 v65, 0xffff0000, v158
	v_mul_f32_e32 v62, v62, v64
	v_mul_f32_e32 v63, v63, v65
	v_cvt_pk_bf16_f32 v60, v62, v63
	v_add_f32_e32 v62, v36, v172
	v_add_f32_e32 v63, v37, v172
	v_lshlrev_b32_e32 v64, 16, v143
	v_and_b32_e32 v65, 0xffff0000, v143
	v_mul_f32_e32 v62, v62, v64
	v_mul_f32_e32 v63, v63, v65
	v_lshlrev_b32_e32 v64, 16, v159
	v_and_b32_e32 v65, 0xffff0000, v159
	v_mul_f32_e32 v62, v62, v64
	v_mul_f32_e32 v63, v63, v65
	v_cvt_pk_bf16_f32 v61, v62, v63
	global_store_dwordx4 v[178:179], v[58:61], off
	s_waitcnt vmcnt(14)
	v_mfma_f32_16x16x32_bf16 v[38:41], v[2:5], v[92:95], 0
	v_mfma_f32_16x16x32_bf16 v[34:37], v[6:9], v[92:95], 0
	v_mfma_f32_16x16x32_bf16 v[38:41], v[10:13], v[96:99], v[38:41]
	v_mfma_f32_16x16x32_bf16 v[34:37], v[14:17], v[96:99], v[34:37]
	v_mfma_f32_16x16x32_bf16 v[38:41], v[18:21], v[100:103], v[38:41]
	v_mfma_f32_16x16x32_bf16 v[34:37], v[22:25], v[100:103], v[34:37]
	v_mfma_f32_16x16x32_bf16 v[38:41], v[26:29], v[104:107], v[38:41]
	v_mfma_f32_16x16x32_bf16 v[34:37], v[30:33], v[104:107], v[34:37]
	v_add_u32_e32 v180, 80, v50
	v_ashrrev_i32_e32 v181, 31, v180
	v_lshlrev_b64 v[178:179], 11, v[180:181]
	v_lshl_add_u64 v[178:179], v[54:55], 0, v[178:179]
	s_nop 7
	v_add_f32_e32 v62, v38, v173
	v_add_f32_e32 v63, v39, v173
	v_lshlrev_b32_e32 v64, 16, v144
	v_and_b32_e32 v65, 0xffff0000, v144
	v_mul_f32_e32 v62, v62, v64
	v_mul_f32_e32 v63, v63, v65
	v_lshlrev_b32_e32 v64, 16, v160
	v_and_b32_e32 v65, 0xffff0000, v160
	v_mul_f32_e32 v62, v62, v64
	v_mul_f32_e32 v63, v63, v65
	v_cvt_pk_bf16_f32 v58, v62, v63
	v_add_f32_e32 v62, v40, v173
	v_add_f32_e32 v63, v41, v173
	v_lshlrev_b32_e32 v64, 16, v145
	v_and_b32_e32 v65, 0xffff0000, v145
	v_mul_f32_e32 v62, v62, v64
	v_mul_f32_e32 v63, v63, v65
	v_lshlrev_b32_e32 v64, 16, v161
	v_and_b32_e32 v65, 0xffff0000, v161
	v_mul_f32_e32 v62, v62, v64
	v_mul_f32_e32 v63, v63, v65
	v_cvt_pk_bf16_f32 v59, v62, v63
	v_add_f32_e32 v62, v34, v173
	v_add_f32_e32 v63, v35, v173
	v_lshlrev_b32_e32 v64, 16, v146
	v_and_b32_e32 v65, 0xffff0000, v146
	v_mul_f32_e32 v62, v62, v64
	v_mul_f32_e32 v63, v63, v65
	v_lshlrev_b32_e32 v64, 16, v162
	v_and_b32_e32 v65, 0xffff0000, v162
	v_mul_f32_e32 v62, v62, v64
	v_mul_f32_e32 v63, v63, v65
	v_cvt_pk_bf16_f32 v60, v62, v63
	v_add_f32_e32 v62, v36, v173
	v_add_f32_e32 v63, v37, v173
	v_lshlrev_b32_e32 v64, 16, v147
	v_and_b32_e32 v65, 0xffff0000, v147
	v_mul_f32_e32 v62, v62, v64
	v_mul_f32_e32 v63, v63, v65
	v_lshlrev_b32_e32 v64, 16, v163
	v_and_b32_e32 v65, 0xffff0000, v163
	v_mul_f32_e32 v62, v62, v64
	v_mul_f32_e32 v63, v63, v65
	v_cvt_pk_bf16_f32 v61, v62, v63
	global_store_dwordx4 v[178:179], v[58:61], off
	s_waitcnt vmcnt(7)
	v_mfma_f32_16x16x32_bf16 v[38:41], v[2:5], v[108:111], 0
	v_mfma_f32_16x16x32_bf16 v[34:37], v[6:9], v[108:111], 0
	v_mfma_f32_16x16x32_bf16 v[38:41], v[10:13], v[112:115], v[38:41]
	v_mfma_f32_16x16x32_bf16 v[34:37], v[14:17], v[112:115], v[34:37]
	v_mfma_f32_16x16x32_bf16 v[38:41], v[18:21], v[116:119], v[38:41]
	v_mfma_f32_16x16x32_bf16 v[34:37], v[22:25], v[116:119], v[34:37]
	v_mfma_f32_16x16x32_bf16 v[38:41], v[26:29], v[120:123], v[38:41]
	v_mfma_f32_16x16x32_bf16 v[34:37], v[30:33], v[120:123], v[34:37]
	v_add_u32_e32 v180, 96, v50
	v_ashrrev_i32_e32 v181, 31, v180
	v_lshlrev_b64 v[178:179], 11, v[180:181]
	v_lshl_add_u64 v[178:179], v[54:55], 0, v[178:179]
	s_nop 7
	v_add_f32_e32 v62, v38, v174
	v_add_f32_e32 v63, v39, v174
	v_lshlrev_b32_e32 v64, 16, v148
	v_and_b32_e32 v65, 0xffff0000, v148
	v_mul_f32_e32 v62, v62, v64
	v_mul_f32_e32 v63, v63, v65
	v_lshlrev_b32_e32 v64, 16, v164
	v_and_b32_e32 v65, 0xffff0000, v164
	v_mul_f32_e32 v62, v62, v64
	v_mul_f32_e32 v63, v63, v65
	v_cvt_pk_bf16_f32 v58, v62, v63
	v_add_f32_e32 v62, v40, v174
	v_add_f32_e32 v63, v41, v174
	v_lshlrev_b32_e32 v64, 16, v149
	v_and_b32_e32 v65, 0xffff0000, v149
	v_mul_f32_e32 v62, v62, v64
	v_mul_f32_e32 v63, v63, v65
	v_lshlrev_b32_e32 v64, 16, v165
	v_and_b32_e32 v65, 0xffff0000, v165
	v_mul_f32_e32 v62, v62, v64
	v_mul_f32_e32 v63, v63, v65
	v_cvt_pk_bf16_f32 v59, v62, v63
	v_add_f32_e32 v62, v34, v174
	v_add_f32_e32 v63, v35, v174
	v_lshlrev_b32_e32 v64, 16, v150
	v_and_b32_e32 v65, 0xffff0000, v150
	v_mul_f32_e32 v62, v62, v64
	v_mul_f32_e32 v63, v63, v65
	v_lshlrev_b32_e32 v64, 16, v166
	v_and_b32_e32 v65, 0xffff0000, v166
	v_mul_f32_e32 v62, v62, v64
	v_mul_f32_e32 v63, v63, v65
	v_cvt_pk_bf16_f32 v60, v62, v63
	v_add_f32_e32 v62, v36, v174
	v_add_f32_e32 v63, v37, v174
	v_lshlrev_b32_e32 v64, 16, v151
	v_and_b32_e32 v65, 0xffff0000, v151
	v_mul_f32_e32 v62, v62, v64
	v_mul_f32_e32 v63, v63, v65
	v_lshlrev_b32_e32 v64, 16, v167
	v_and_b32_e32 v65, 0xffff0000, v167
	v_mul_f32_e32 v62, v62, v64
	v_mul_f32_e32 v63, v63, v65
	v_cvt_pk_bf16_f32 v61, v62, v63
	global_store_dwordx4 v[178:179], v[58:61], off
	s_waitcnt vmcnt(0)
	v_mfma_f32_16x16x32_bf16 v[38:41], v[2:5], v[124:127], 0
	v_mfma_f32_16x16x32_bf16 v[34:37], v[6:9], v[124:127], 0
	v_mfma_f32_16x16x32_bf16 v[38:41], v[10:13], v[128:131], v[38:41]
	v_mfma_f32_16x16x32_bf16 v[34:37], v[14:17], v[128:131], v[34:37]
	v_mfma_f32_16x16x32_bf16 v[38:41], v[18:21], v[132:135], v[38:41]
	v_mfma_f32_16x16x32_bf16 v[34:37], v[22:25], v[132:135], v[34:37]
	v_mfma_f32_16x16x32_bf16 v[38:41], v[26:29], v[136:139], v[38:41]
	v_mfma_f32_16x16x32_bf16 v[34:37], v[30:33], v[136:139], v[34:37]
	v_add_u32_e32 v180, 112, v50
	v_ashrrev_i32_e32 v181, 31, v180
	v_lshlrev_b64 v[178:179], 11, v[180:181]
	v_lshl_add_u64 v[178:179], v[54:55], 0, v[178:179]
	s_nop 7
	v_add_f32_e32 v62, v38, v175
	v_add_f32_e32 v63, v39, v175
	v_lshlrev_b32_e32 v64, 16, v152
	v_and_b32_e32 v65, 0xffff0000, v152
	v_mul_f32_e32 v62, v62, v64
	v_mul_f32_e32 v63, v63, v65
	v_lshlrev_b32_e32 v64, 16, v168
	v_and_b32_e32 v65, 0xffff0000, v168
	v_mul_f32_e32 v62, v62, v64
	v_mul_f32_e32 v63, v63, v65
	v_cvt_pk_bf16_f32 v58, v62, v63
	v_add_f32_e32 v62, v40, v175
	v_add_f32_e32 v63, v41, v175
	v_lshlrev_b32_e32 v64, 16, v153
	v_and_b32_e32 v65, 0xffff0000, v153
	v_mul_f32_e32 v62, v62, v64
	v_mul_f32_e32 v63, v63, v65
	v_lshlrev_b32_e32 v64, 16, v169
	v_and_b32_e32 v65, 0xffff0000, v169
	v_mul_f32_e32 v62, v62, v64
	v_mul_f32_e32 v63, v63, v65
	v_cvt_pk_bf16_f32 v59, v62, v63
	v_add_f32_e32 v62, v34, v175
	v_add_f32_e32 v63, v35, v175
	v_lshlrev_b32_e32 v64, 16, v154
	v_and_b32_e32 v65, 0xffff0000, v154
	v_mul_f32_e32 v62, v62, v64
	v_mul_f32_e32 v63, v63, v65
	v_lshlrev_b32_e32 v64, 16, v170
	v_and_b32_e32 v65, 0xffff0000, v170
	v_mul_f32_e32 v62, v62, v64
	v_mul_f32_e32 v63, v63, v65
	v_cvt_pk_bf16_f32 v60, v62, v63
	v_add_f32_e32 v62, v36, v175
	v_add_f32_e32 v63, v37, v175
	v_lshlrev_b32_e32 v64, 16, v155
	v_and_b32_e32 v65, 0xffff0000, v155
	v_mul_f32_e32 v62, v62, v64
	v_mul_f32_e32 v63, v63, v65
	v_lshlrev_b32_e32 v64, 16, v171
	v_and_b32_e32 v65, 0xffff0000, v171
	v_mul_f32_e32 v62, v62, v64
	v_mul_f32_e32 v63, v63, v65
	v_cvt_pk_bf16_f32 v61, v62, v63
	global_store_dwordx4 v[178:179], v[58:61], off
	s_add_i32 s8, s8, s88
	s_add_i32 s7, s7, s13
	s_cmp_ge_i32 s8, s4
	s_cbranch_scc0 .LBB0_274
